# ph8 epilogue conv: the row shifts ride on v_fmac_f32_dpp (2 pk_fma + 16 fmac_dpp per 4-column block instead of 2 copies + 16 v_mov_dpp + 6 pk_fma); carry-in rows via lane-masked coefficients; same per
# speedup vs baseline: 1.0085x; 1.0041x over previous
.LBB0_989:
	s_or_b64 exec, exec, s[62:63]
	v_and_b32_e32 v228, 15, v178
	v_cmp_eq_u32_e64 s[98:99], 0, v228
	v_cmp_gt_u32_e64 s[100:101], 2, v228
	s_lshl_b32 s28, s8, 7
	v_or_b32_e32 v204, s28, v180
	v_ashrrev_i32_e32 v205, 31, v204
	v_lshlrev_b64 v[68:69], 2, v[204:205]
	s_waitcnt lgkmcnt(0)
	s_barrier
	v_lshl_add_u64 v[206:207], s[24:25], 0, v[68:69]
	v_lshl_add_u64 v[70:71], s[36:37], 0, v[68:69]
	v_lshl_add_u64 v[208:209], s[26:27], 0, v[68:69]
	global_load_dwordx4 v[150:153], v[206:207], off
	v_lshl_add_u64 v[76:77], s[38:39], 0, v[68:69]
	global_load_dwordx4 v[146:149], v[70:71], off
	global_load_dwordx4 v[142:145], v[76:77], off
	global_load_dwordx4 v[154:157], v[208:209], off
	v_cndmask_b32_e64 v68, 0, 1, s[48:49]
	v_mov_b32_e32 v136, 0
	v_cmp_ne_u32_e64 s[8:9], 1, v68
	s_andn2_b64 vcc, exec, s[48:49]
	v_mov_b32_e32 v158, 0
	v_mov_b32_e32 v159, 0
	v_mov_b32_e32 v160, 0
	v_mov_b32_e32 v161, 0
	s_cbranch_vccnz .LBB0_991
	ds_read_b128 v[158:161], v212
.LBB0_991:
	s_waitcnt vmcnt(0)
	v_cndmask_b32_e64 v220, 0, v146, s[98:99]
	v_cndmask_b32_e64 v224, 0, v142, s[100:101]
	v_cndmask_b32_e64 v221, 0, v147, s[98:99]
	v_cndmask_b32_e64 v225, 0, v143, s[100:101]
	v_cndmask_b32_e64 v222, 0, v148, s[98:99]
	v_cndmask_b32_e64 v226, 0, v144, s[100:101]
	v_cndmask_b32_e64 v223, 0, v149, s[98:99]
	v_cndmask_b32_e64 v227, 0, v145, s[100:101]
	v_pk_fma_f32 v[76:77], v[150:151], v[112:113], v[154:155]
	v_pk_fma_f32 v[78:79], v[152:153], v[114:115], v[156:157]
	s_nop 0
	v_fmac_f32_dpp v76, v112, v146 row_shr:1 row_mask:0xf bank_mask:0xf
	v_fmac_f32_dpp v77, v113, v147 row_shr:1 row_mask:0xf bank_mask:0xf
	v_fmac_f32_dpp v78, v114, v148 row_shr:1 row_mask:0xf bank_mask:0xf
	v_fmac_f32_dpp v79, v115, v149 row_shr:1 row_mask:0xf bank_mask:0xf
	v_fmac_f32_dpp v76, v112, v142 row_shr:2 row_mask:0xf bank_mask:0xf
	v_fmac_f32_dpp v77, v113, v143 row_shr:2 row_mask:0xf bank_mask:0xf
	v_fmac_f32_dpp v78, v114, v144 row_shr:2 row_mask:0xf bank_mask:0xf
	v_fmac_f32_dpp v79, v115, v145 row_shr:2 row_mask:0xf bank_mask:0xf
	v_fmac_f32_dpp v76, v128, v220 row_ror:1 row_mask:0xf bank_mask:0xf bound_ctrl:1
	v_fmac_f32_dpp v77, v129, v221 row_ror:1 row_mask:0xf bank_mask:0xf bound_ctrl:1
	v_fmac_f32_dpp v78, v130, v222 row_ror:1 row_mask:0xf bank_mask:0xf bound_ctrl:1
	v_fmac_f32_dpp v79, v131, v223 row_ror:1 row_mask:0xf bank_mask:0xf bound_ctrl:1
	v_fmac_f32_dpp v76, v128, v224 row_ror:2 row_mask:0xf bank_mask:0xf bound_ctrl:1
	v_fmac_f32_dpp v77, v129, v225 row_ror:2 row_mask:0xf bank_mask:0xf bound_ctrl:1
	v_fmac_f32_dpp v78, v130, v226 row_ror:2 row_mask:0xf bank_mask:0xf bound_ctrl:1
	v_fmac_f32_dpp v79, v131, v227 row_ror:2 row_mask:0xf bank_mask:0xf bound_ctrl:1
	s_nop 0
	v_pk_fma_f32 v[100:101], v[150:151], v[128:129], v[154:155]
	v_pk_fma_f32 v[102:103], v[152:153], v[130:131], v[156:157]
	s_nop 0
	v_fmac_f32_dpp v100, v128, v146 row_shr:1 row_mask:0xf bank_mask:0xf
	v_fmac_f32_dpp v101, v129, v147 row_shr:1 row_mask:0xf bank_mask:0xf
	v_fmac_f32_dpp v102, v130, v148 row_shr:1 row_mask:0xf bank_mask:0xf
	v_fmac_f32_dpp v103, v131, v149 row_shr:1 row_mask:0xf bank_mask:0xf
	v_fmac_f32_dpp v100, v128, v142 row_shr:2 row_mask:0xf bank_mask:0xf
	v_fmac_f32_dpp v101, v129, v143 row_shr:2 row_mask:0xf bank_mask:0xf
	v_fmac_f32_dpp v102, v130, v144 row_shr:2 row_mask:0xf bank_mask:0xf
	v_fmac_f32_dpp v103, v131, v145 row_shr:2 row_mask:0xf bank_mask:0xf
	v_fmac_f32_dpp v100, v124, v220 row_ror:1 row_mask:0xf bank_mask:0xf bound_ctrl:1
	v_fmac_f32_dpp v101, v125, v221 row_ror:1 row_mask:0xf bank_mask:0xf bound_ctrl:1
	v_fmac_f32_dpp v102, v126, v222 row_ror:1 row_mask:0xf bank_mask:0xf bound_ctrl:1
	v_fmac_f32_dpp v103, v127, v223 row_ror:1 row_mask:0xf bank_mask:0xf bound_ctrl:1
	v_fmac_f32_dpp v100, v124, v224 row_ror:2 row_mask:0xf bank_mask:0xf bound_ctrl:1
	v_fmac_f32_dpp v101, v125, v225 row_ror:2 row_mask:0xf bank_mask:0xf bound_ctrl:1
	v_fmac_f32_dpp v102, v126, v226 row_ror:2 row_mask:0xf bank_mask:0xf bound_ctrl:1
	v_fmac_f32_dpp v103, v127, v227 row_ror:2 row_mask:0xf bank_mask:0xf bound_ctrl:1
	s_nop 0
	v_pk_fma_f32 v[68:69], v[150:151], v[124:125], v[154:155]
	v_pk_fma_f32 v[70:71], v[152:153], v[126:127], v[156:157]
	s_nop 0
	v_fmac_f32_dpp v68, v124, v146 row_shr:1 row_mask:0xf bank_mask:0xf
	v_fmac_f32_dpp v69, v125, v147 row_shr:1 row_mask:0xf bank_mask:0xf
	v_fmac_f32_dpp v70, v126, v148 row_shr:1 row_mask:0xf bank_mask:0xf
	v_fmac_f32_dpp v71, v127, v149 row_shr:1 row_mask:0xf bank_mask:0xf
	v_fmac_f32_dpp v68, v124, v142 row_shr:2 row_mask:0xf bank_mask:0xf
	v_fmac_f32_dpp v69, v125, v143 row_shr:2 row_mask:0xf bank_mask:0xf
	v_fmac_f32_dpp v70, v126, v144 row_shr:2 row_mask:0xf bank_mask:0xf
	v_fmac_f32_dpp v71, v127, v145 row_shr:2 row_mask:0xf bank_mask:0xf
	v_fmac_f32_dpp v68, v116, v220 row_ror:1 row_mask:0xf bank_mask:0xf bound_ctrl:1
	v_fmac_f32_dpp v69, v117, v221 row_ror:1 row_mask:0xf bank_mask:0xf bound_ctrl:1
	v_fmac_f32_dpp v70, v118, v222 row_ror:1 row_mask:0xf bank_mask:0xf bound_ctrl:1
	v_fmac_f32_dpp v71, v119, v223 row_ror:1 row_mask:0xf bank_mask:0xf bound_ctrl:1
	v_fmac_f32_dpp v68, v116, v224 row_ror:2 row_mask:0xf bank_mask:0xf bound_ctrl:1
	v_fmac_f32_dpp v69, v117, v225 row_ror:2 row_mask:0xf bank_mask:0xf bound_ctrl:1
	v_fmac_f32_dpp v70, v118, v226 row_ror:2 row_mask:0xf bank_mask:0xf bound_ctrl:1
	v_fmac_f32_dpp v71, v119, v227 row_ror:2 row_mask:0xf bank_mask:0xf bound_ctrl:1
	s_nop 0
	s_waitcnt lgkmcnt(0)
	v_pk_fma_f32 v[124:125], v[150:151], v[116:117], v[154:155]
	v_pk_fma_f32 v[126:127], v[152:153], v[118:119], v[156:157]
	s_nop 0
	v_fmac_f32_dpp v124, v116, v146 row_shr:1 row_mask:0xf bank_mask:0xf
	v_fmac_f32_dpp v125, v117, v147 row_shr:1 row_mask:0xf bank_mask:0xf
	v_fmac_f32_dpp v126, v118, v148 row_shr:1 row_mask:0xf bank_mask:0xf
	v_fmac_f32_dpp v127, v119, v149 row_shr:1 row_mask:0xf bank_mask:0xf
	v_fmac_f32_dpp v124, v116, v142 row_shr:2 row_mask:0xf bank_mask:0xf
	v_fmac_f32_dpp v125, v117, v143 row_shr:2 row_mask:0xf bank_mask:0xf
	v_fmac_f32_dpp v126, v118, v144 row_shr:2 row_mask:0xf bank_mask:0xf
	v_fmac_f32_dpp v127, v119, v145 row_shr:2 row_mask:0xf bank_mask:0xf
	v_fmac_f32_dpp v124, v158, v220 row_ror:1 row_mask:0xf bank_mask:0xf bound_ctrl:1
	v_fmac_f32_dpp v125, v159, v221 row_ror:1 row_mask:0xf bank_mask:0xf bound_ctrl:1
	v_fmac_f32_dpp v126, v160, v222 row_ror:1 row_mask:0xf bank_mask:0xf bound_ctrl:1
	v_fmac_f32_dpp v127, v161, v223 row_ror:1 row_mask:0xf bank_mask:0xf bound_ctrl:1
	v_fmac_f32_dpp v124, v158, v224 row_ror:2 row_mask:0xf bank_mask:0xf bound_ctrl:1
	v_fmac_f32_dpp v125, v159, v225 row_ror:2 row_mask:0xf bank_mask:0xf bound_ctrl:1
	v_fmac_f32_dpp v126, v160, v226 row_ror:2 row_mask:0xf bank_mask:0xf bound_ctrl:1
	v_fmac_f32_dpp v127, v161, v227 row_ror:2 row_mask:0xf bank_mask:0xf bound_ctrl:1
	s_nop 0
	ds_read_b128 v[128:131], v212 offset:4096
	v_pk_fma_f32 v[230:231], v[150:151], v[92:93], v[154:155]
	v_pk_fma_f32 v[232:233], v[152:153], v[94:95], v[156:157]
	s_nop 0
	v_fmac_f32_dpp v230, v92, v146 row_shr:1 row_mask:0xf bank_mask:0xf
	v_fmac_f32_dpp v231, v93, v147 row_shr:1 row_mask:0xf bank_mask:0xf
	v_fmac_f32_dpp v232, v94, v148 row_shr:1 row_mask:0xf bank_mask:0xf
	v_fmac_f32_dpp v233, v95, v149 row_shr:1 row_mask:0xf bank_mask:0xf
	v_fmac_f32_dpp v230, v92, v142 row_shr:2 row_mask:0xf bank_mask:0xf
	v_fmac_f32_dpp v231, v93, v143 row_shr:2 row_mask:0xf bank_mask:0xf
	v_fmac_f32_dpp v232, v94, v144 row_shr:2 row_mask:0xf bank_mask:0xf
	v_fmac_f32_dpp v233, v95, v145 row_shr:2 row_mask:0xf bank_mask:0xf
	v_fmac_f32_dpp v230, v138, v220 row_ror:1 row_mask:0xf bank_mask:0xf bound_ctrl:1
	v_fmac_f32_dpp v231, v139, v221 row_ror:1 row_mask:0xf bank_mask:0xf bound_ctrl:1
	v_fmac_f32_dpp v232, v140, v222 row_ror:1 row_mask:0xf bank_mask:0xf bound_ctrl:1
	v_fmac_f32_dpp v233, v141, v223 row_ror:1 row_mask:0xf bank_mask:0xf bound_ctrl:1
	v_fmac_f32_dpp v230, v138, v224 row_ror:2 row_mask:0xf bank_mask:0xf bound_ctrl:1
	v_fmac_f32_dpp v231, v139, v225 row_ror:2 row_mask:0xf bank_mask:0xf bound_ctrl:1
	v_fmac_f32_dpp v232, v140, v226 row_ror:2 row_mask:0xf bank_mask:0xf bound_ctrl:1
	v_fmac_f32_dpp v233, v141, v227 row_ror:2 row_mask:0xf bank_mask:0xf bound_ctrl:1
	v_mov_b64_e32 v[92:93], v[230:231]
	v_mov_b64_e32 v[94:95], v[232:233]
	s_nop 0
	v_pk_fma_f32 v[112:113], v[150:151], v[138:139], v[154:155]
	v_pk_fma_f32 v[114:115], v[152:153], v[140:141], v[156:157]
	s_nop 0
	v_fmac_f32_dpp v112, v138, v146 row_shr:1 row_mask:0xf bank_mask:0xf
	v_fmac_f32_dpp v113, v139, v147 row_shr:1 row_mask:0xf bank_mask:0xf
	v_fmac_f32_dpp v114, v140, v148 row_shr:1 row_mask:0xf bank_mask:0xf
	v_fmac_f32_dpp v115, v141, v149 row_shr:1 row_mask:0xf bank_mask:0xf
	v_fmac_f32_dpp v112, v138, v142 row_shr:2 row_mask:0xf bank_mask:0xf
	v_fmac_f32_dpp v113, v139, v143 row_shr:2 row_mask:0xf bank_mask:0xf
	v_fmac_f32_dpp v114, v140, v144 row_shr:2 row_mask:0xf bank_mask:0xf
	v_fmac_f32_dpp v115, v141, v145 row_shr:2 row_mask:0xf bank_mask:0xf
	v_fmac_f32_dpp v112, v132, v220 row_ror:1 row_mask:0xf bank_mask:0xf bound_ctrl:1
	v_fmac_f32_dpp v113, v133, v221 row_ror:1 row_mask:0xf bank_mask:0xf bound_ctrl:1
	v_fmac_f32_dpp v114, v134, v222 row_ror:1 row_mask:0xf bank_mask:0xf bound_ctrl:1
	v_fmac_f32_dpp v115, v135, v223 row_ror:1 row_mask:0xf bank_mask:0xf bound_ctrl:1
	v_fmac_f32_dpp v112, v132, v224 row_ror:2 row_mask:0xf bank_mask:0xf bound_ctrl:1
	v_fmac_f32_dpp v113, v133, v225 row_ror:2 row_mask:0xf bank_mask:0xf bound_ctrl:1
	v_fmac_f32_dpp v114, v134, v226 row_ror:2 row_mask:0xf bank_mask:0xf bound_ctrl:1
	v_fmac_f32_dpp v115, v135, v227 row_ror:2 row_mask:0xf bank_mask:0xf bound_ctrl:1
	s_nop 0
	v_pk_fma_f32 v[116:117], v[150:151], v[132:133], v[154:155]
	v_pk_fma_f32 v[118:119], v[152:153], v[134:135], v[156:157]
	s_nop 0
	v_fmac_f32_dpp v116, v132, v146 row_shr:1 row_mask:0xf bank_mask:0xf
	v_fmac_f32_dpp v117, v133, v147 row_shr:1 row_mask:0xf bank_mask:0xf
	v_fmac_f32_dpp v118, v134, v148 row_shr:1 row_mask:0xf bank_mask:0xf
	v_fmac_f32_dpp v119, v135, v149 row_shr:1 row_mask:0xf bank_mask:0xf
	v_fmac_f32_dpp v116, v132, v142 row_shr:2 row_mask:0xf bank_mask:0xf
	v_fmac_f32_dpp v117, v133, v143 row_shr:2 row_mask:0xf bank_mask:0xf
	v_fmac_f32_dpp v118, v134, v144 row_shr:2 row_mask:0xf bank_mask:0xf
	v_fmac_f32_dpp v119, v135, v145 row_shr:2 row_mask:0xf bank_mask:0xf
	v_fmac_f32_dpp v116, v120, v220 row_ror:1 row_mask:0xf bank_mask:0xf bound_ctrl:1
	v_fmac_f32_dpp v117, v121, v221 row_ror:1 row_mask:0xf bank_mask:0xf bound_ctrl:1
	v_fmac_f32_dpp v118, v122, v222 row_ror:1 row_mask:0xf bank_mask:0xf bound_ctrl:1
	v_fmac_f32_dpp v119, v123, v223 row_ror:1 row_mask:0xf bank_mask:0xf bound_ctrl:1
	v_fmac_f32_dpp v116, v120, v224 row_ror:2 row_mask:0xf bank_mask:0xf bound_ctrl:1
	v_fmac_f32_dpp v117, v121, v225 row_ror:2 row_mask:0xf bank_mask:0xf bound_ctrl:1
	v_fmac_f32_dpp v118, v122, v226 row_ror:2 row_mask:0xf bank_mask:0xf bound_ctrl:1
	v_fmac_f32_dpp v119, v123, v227 row_ror:2 row_mask:0xf bank_mask:0xf bound_ctrl:1
	s_nop 0
	s_waitcnt lgkmcnt(0)
	v_pk_fma_f32 v[230:231], v[150:151], v[120:121], v[154:155]
	v_pk_fma_f32 v[232:233], v[152:153], v[122:123], v[156:157]
	s_nop 0
	v_fmac_f32_dpp v230, v120, v146 row_shr:1 row_mask:0xf bank_mask:0xf
	v_fmac_f32_dpp v231, v121, v147 row_shr:1 row_mask:0xf bank_mask:0xf
	v_fmac_f32_dpp v232, v122, v148 row_shr:1 row_mask:0xf bank_mask:0xf
	v_fmac_f32_dpp v233, v123, v149 row_shr:1 row_mask:0xf bank_mask:0xf
	v_fmac_f32_dpp v230, v120, v142 row_shr:2 row_mask:0xf bank_mask:0xf
	v_fmac_f32_dpp v231, v121, v143 row_shr:2 row_mask:0xf bank_mask:0xf
	v_fmac_f32_dpp v232, v122, v144 row_shr:2 row_mask:0xf bank_mask:0xf
	v_fmac_f32_dpp v233, v123, v145 row_shr:2 row_mask:0xf bank_mask:0xf
	v_fmac_f32_dpp v230, v128, v220 row_ror:1 row_mask:0xf bank_mask:0xf bound_ctrl:1
	v_fmac_f32_dpp v231, v129, v221 row_ror:1 row_mask:0xf bank_mask:0xf bound_ctrl:1
	v_fmac_f32_dpp v232, v130, v222 row_ror:1 row_mask:0xf bank_mask:0xf bound_ctrl:1
	v_fmac_f32_dpp v233, v131, v223 row_ror:1 row_mask:0xf bank_mask:0xf bound_ctrl:1
	v_fmac_f32_dpp v230, v128, v224 row_ror:2 row_mask:0xf bank_mask:0xf bound_ctrl:1
	v_fmac_f32_dpp v231, v129, v225 row_ror:2 row_mask:0xf bank_mask:0xf bound_ctrl:1
	v_fmac_f32_dpp v232, v130, v226 row_ror:2 row_mask:0xf bank_mask:0xf bound_ctrl:1
	v_fmac_f32_dpp v233, v131, v227 row_ror:2 row_mask:0xf bank_mask:0xf bound_ctrl:1
	v_mov_b64_e32 v[120:121], v[230:231]
	v_mov_b64_e32 v[122:123], v[232:233]
	s_nop 0
	v_add_u32_e32 v128, 0xc00, v204
	v_ashrrev_i32_e32 v129, 31, v128
	v_lshlrev_b64 v[128:129], 2, v[128:129]
	v_lshl_add_u64 v[130:131], s[24:25], 0, v[128:129]
	v_lshl_add_u64 v[132:133], s[36:37], 0, v[128:129]
	global_load_dwordx4 v[144:147], v[130:131], off
	global_load_dwordx4 v[140:143], v[132:133], off
	v_lshl_add_u64 v[130:131], s[38:39], 0, v[128:129]
	v_lshl_add_u64 v[128:129], s[26:27], 0, v[128:129]
	global_load_dwordx4 v[132:135], v[130:131], off
	global_load_dwordx4 v[148:151], v[128:129], off
	s_and_b64 vcc, exec, s[8:9]
	v_mov_b32_e32 v137, 0
	v_mov_b32_e32 v138, 0
	v_mov_b32_e32 v139, 0
	s_cbranch_vccnz .LBB0_993
	ds_read_b128 v[136:139], v212 offset:512
.LBB0_993:
	s_waitcnt vmcnt(0)
	v_cndmask_b32_e64 v220, 0, v140, s[98:99]
	v_cndmask_b32_e64 v224, 0, v132, s[100:101]
	v_cndmask_b32_e64 v221, 0, v141, s[98:99]
	v_cndmask_b32_e64 v225, 0, v133, s[100:101]
	v_cndmask_b32_e64 v222, 0, v142, s[98:99]
	v_cndmask_b32_e64 v226, 0, v134, s[100:101]
	v_cndmask_b32_e64 v223, 0, v143, s[98:99]
	v_cndmask_b32_e64 v227, 0, v135, s[100:101]
	v_pk_fma_f32 v[230:231], v[144:145], v[108:109], v[148:149]
	v_pk_fma_f32 v[232:233], v[146:147], v[110:111], v[150:151]
	s_nop 0
	v_fmac_f32_dpp v230, v108, v140 row_shr:1 row_mask:0xf bank_mask:0xf
	v_fmac_f32_dpp v231, v109, v141 row_shr:1 row_mask:0xf bank_mask:0xf
	v_fmac_f32_dpp v232, v110, v142 row_shr:1 row_mask:0xf bank_mask:0xf
	v_fmac_f32_dpp v233, v111, v143 row_shr:1 row_mask:0xf bank_mask:0xf
	v_fmac_f32_dpp v230, v108, v132 row_shr:2 row_mask:0xf bank_mask:0xf
	v_fmac_f32_dpp v231, v109, v133 row_shr:2 row_mask:0xf bank_mask:0xf
	v_fmac_f32_dpp v232, v110, v134 row_shr:2 row_mask:0xf bank_mask:0xf
	v_fmac_f32_dpp v233, v111, v135 row_shr:2 row_mask:0xf bank_mask:0xf
	v_fmac_f32_dpp v230, v104, v220 row_ror:1 row_mask:0xf bank_mask:0xf bound_ctrl:1
	v_fmac_f32_dpp v231, v105, v221 row_ror:1 row_mask:0xf bank_mask:0xf bound_ctrl:1
	v_fmac_f32_dpp v232, v106, v222 row_ror:1 row_mask:0xf bank_mask:0xf bound_ctrl:1
	v_fmac_f32_dpp v233, v107, v223 row_ror:1 row_mask:0xf bank_mask:0xf bound_ctrl:1
	v_fmac_f32_dpp v230, v104, v224 row_ror:2 row_mask:0xf bank_mask:0xf bound_ctrl:1
	v_fmac_f32_dpp v231, v105, v225 row_ror:2 row_mask:0xf bank_mask:0xf bound_ctrl:1
	v_fmac_f32_dpp v232, v106, v226 row_ror:2 row_mask:0xf bank_mask:0xf bound_ctrl:1
	v_fmac_f32_dpp v233, v107, v227 row_ror:2 row_mask:0xf bank_mask:0xf bound_ctrl:1
	v_mov_b64_e32 v[108:109], v[230:231]
	v_mov_b64_e32 v[110:111], v[232:233]
	s_nop 0
	v_pk_fma_f32 v[128:129], v[144:145], v[104:105], v[148:149]
	v_pk_fma_f32 v[130:131], v[146:147], v[106:107], v[150:151]
	s_nop 0
	v_fmac_f32_dpp v128, v104, v140 row_shr:1 row_mask:0xf bank_mask:0xf
	v_fmac_f32_dpp v129, v105, v141 row_shr:1 row_mask:0xf bank_mask:0xf
	v_fmac_f32_dpp v130, v106, v142 row_shr:1 row_mask:0xf bank_mask:0xf
	v_fmac_f32_dpp v131, v107, v143 row_shr:1 row_mask:0xf bank_mask:0xf
	v_fmac_f32_dpp v128, v104, v132 row_shr:2 row_mask:0xf bank_mask:0xf
	v_fmac_f32_dpp v129, v105, v133 row_shr:2 row_mask:0xf bank_mask:0xf
	v_fmac_f32_dpp v130, v106, v134 row_shr:2 row_mask:0xf bank_mask:0xf
	v_fmac_f32_dpp v131, v107, v135 row_shr:2 row_mask:0xf bank_mask:0xf
	v_fmac_f32_dpp v128, v88, v220 row_ror:1 row_mask:0xf bank_mask:0xf bound_ctrl:1
	v_fmac_f32_dpp v129, v89, v221 row_ror:1 row_mask:0xf bank_mask:0xf bound_ctrl:1
	v_fmac_f32_dpp v130, v90, v222 row_ror:1 row_mask:0xf bank_mask:0xf bound_ctrl:1
	v_fmac_f32_dpp v131, v91, v223 row_ror:1 row_mask:0xf bank_mask:0xf bound_ctrl:1
	v_fmac_f32_dpp v128, v88, v224 row_ror:2 row_mask:0xf bank_mask:0xf bound_ctrl:1
	v_fmac_f32_dpp v129, v89, v225 row_ror:2 row_mask:0xf bank_mask:0xf bound_ctrl:1
	v_fmac_f32_dpp v130, v90, v226 row_ror:2 row_mask:0xf bank_mask:0xf bound_ctrl:1
	v_fmac_f32_dpp v131, v91, v227 row_ror:2 row_mask:0xf bank_mask:0xf bound_ctrl:1
	s_nop 0
	v_pk_fma_f32 v[152:153], v[144:145], v[88:89], v[148:149]
	v_pk_fma_f32 v[154:155], v[146:147], v[90:91], v[150:151]
	s_nop 0
	v_fmac_f32_dpp v152, v88, v140 row_shr:1 row_mask:0xf bank_mask:0xf
	v_fmac_f32_dpp v153, v89, v141 row_shr:1 row_mask:0xf bank_mask:0xf
	v_fmac_f32_dpp v154, v90, v142 row_shr:1 row_mask:0xf bank_mask:0xf
	v_fmac_f32_dpp v155, v91, v143 row_shr:1 row_mask:0xf bank_mask:0xf
	v_fmac_f32_dpp v152, v88, v132 row_shr:2 row_mask:0xf bank_mask:0xf
	v_fmac_f32_dpp v153, v89, v133 row_shr:2 row_mask:0xf bank_mask:0xf
	v_fmac_f32_dpp v154, v90, v134 row_shr:2 row_mask:0xf bank_mask:0xf
	v_fmac_f32_dpp v155, v91, v135 row_shr:2 row_mask:0xf bank_mask:0xf
	v_fmac_f32_dpp v152, v72, v220 row_ror:1 row_mask:0xf bank_mask:0xf bound_ctrl:1
	v_fmac_f32_dpp v153, v73, v221 row_ror:1 row_mask:0xf bank_mask:0xf bound_ctrl:1
	v_fmac_f32_dpp v154, v74, v222 row_ror:1 row_mask:0xf bank_mask:0xf bound_ctrl:1
	v_fmac_f32_dpp v155, v75, v223 row_ror:1 row_mask:0xf bank_mask:0xf bound_ctrl:1
	v_fmac_f32_dpp v152, v72, v224 row_ror:2 row_mask:0xf bank_mask:0xf bound_ctrl:1
	v_fmac_f32_dpp v153, v73, v225 row_ror:2 row_mask:0xf bank_mask:0xf bound_ctrl:1
	v_fmac_f32_dpp v154, v74, v226 row_ror:2 row_mask:0xf bank_mask:0xf bound_ctrl:1
	v_fmac_f32_dpp v155, v75, v227 row_ror:2 row_mask:0xf bank_mask:0xf bound_ctrl:1
	s_nop 0
	s_waitcnt lgkmcnt(0)
	v_pk_fma_f32 v[230:231], v[144:145], v[72:73], v[148:149]
	v_pk_fma_f32 v[232:233], v[146:147], v[74:75], v[150:151]
	s_nop 0
	v_fmac_f32_dpp v230, v72, v140 row_shr:1 row_mask:0xf bank_mask:0xf
	v_fmac_f32_dpp v231, v73, v141 row_shr:1 row_mask:0xf bank_mask:0xf
	v_fmac_f32_dpp v232, v74, v142 row_shr:1 row_mask:0xf bank_mask:0xf
	v_fmac_f32_dpp v233, v75, v143 row_shr:1 row_mask:0xf bank_mask:0xf
	v_fmac_f32_dpp v230, v72, v132 row_shr:2 row_mask:0xf bank_mask:0xf
	v_fmac_f32_dpp v231, v73, v133 row_shr:2 row_mask:0xf bank_mask:0xf
	v_fmac_f32_dpp v232, v74, v134 row_shr:2 row_mask:0xf bank_mask:0xf
	v_fmac_f32_dpp v233, v75, v135 row_shr:2 row_mask:0xf bank_mask:0xf
	v_fmac_f32_dpp v230, v136, v220 row_ror:1 row_mask:0xf bank_mask:0xf bound_ctrl:1
	v_fmac_f32_dpp v231, v137, v221 row_ror:1 row_mask:0xf bank_mask:0xf bound_ctrl:1
	v_fmac_f32_dpp v232, v138, v222 row_ror:1 row_mask:0xf bank_mask:0xf bound_ctrl:1
	v_fmac_f32_dpp v233, v139, v223 row_ror:1 row_mask:0xf bank_mask:0xf bound_ctrl:1
	v_fmac_f32_dpp v230, v136, v224 row_ror:2 row_mask:0xf bank_mask:0xf bound_ctrl:1
	v_fmac_f32_dpp v231, v137, v225 row_ror:2 row_mask:0xf bank_mask:0xf bound_ctrl:1
	v_fmac_f32_dpp v232, v138, v226 row_ror:2 row_mask:0xf bank_mask:0xf bound_ctrl:1
	v_fmac_f32_dpp v233, v139, v227 row_ror:2 row_mask:0xf bank_mask:0xf bound_ctrl:1
	v_mov_b64_e32 v[72:73], v[230:231]
	v_mov_b64_e32 v[74:75], v[232:233]
	s_nop 0
	ds_read_b128 v[136:139], v212 offset:4608
	v_pk_fma_f32 v[104:105], v[144:145], v[64:65], v[148:149]
	v_pk_fma_f32 v[106:107], v[146:147], v[66:67], v[150:151]
	s_nop 0
	v_fmac_f32_dpp v104, v64, v140 row_shr:1 row_mask:0xf bank_mask:0xf
	v_fmac_f32_dpp v105, v65, v141 row_shr:1 row_mask:0xf bank_mask:0xf
	v_fmac_f32_dpp v106, v66, v142 row_shr:1 row_mask:0xf bank_mask:0xf
	v_fmac_f32_dpp v107, v67, v143 row_shr:1 row_mask:0xf bank_mask:0xf
	v_fmac_f32_dpp v104, v64, v132 row_shr:2 row_mask:0xf bank_mask:0xf
	v_fmac_f32_dpp v105, v65, v133 row_shr:2 row_mask:0xf bank_mask:0xf
	v_fmac_f32_dpp v106, v66, v134 row_shr:2 row_mask:0xf bank_mask:0xf
	v_fmac_f32_dpp v107, v67, v135 row_shr:2 row_mask:0xf bank_mask:0xf
	v_fmac_f32_dpp v104, v80, v220 row_ror:1 row_mask:0xf bank_mask:0xf bound_ctrl:1
	v_fmac_f32_dpp v105, v81, v221 row_ror:1 row_mask:0xf bank_mask:0xf bound_ctrl:1
	v_fmac_f32_dpp v106, v82, v222 row_ror:1 row_mask:0xf bank_mask:0xf bound_ctrl:1
	v_fmac_f32_dpp v107, v83, v223 row_ror:1 row_mask:0xf bank_mask:0xf bound_ctrl:1
	v_fmac_f32_dpp v104, v80, v224 row_ror:2 row_mask:0xf bank_mask:0xf bound_ctrl:1
	v_fmac_f32_dpp v105, v81, v225 row_ror:2 row_mask:0xf bank_mask:0xf bound_ctrl:1
	v_fmac_f32_dpp v106, v82, v226 row_ror:2 row_mask:0xf bank_mask:0xf bound_ctrl:1
	v_fmac_f32_dpp v107, v83, v227 row_ror:2 row_mask:0xf bank_mask:0xf bound_ctrl:1
	s_nop 0
	v_pk_fma_f32 v[88:89], v[144:145], v[80:81], v[148:149]
	v_pk_fma_f32 v[90:91], v[146:147], v[82:83], v[150:151]
	s_nop 0
	v_fmac_f32_dpp v88, v80, v140 row_shr:1 row_mask:0xf bank_mask:0xf
	v_fmac_f32_dpp v89, v81, v141 row_shr:1 row_mask:0xf bank_mask:0xf
	v_fmac_f32_dpp v90, v82, v142 row_shr:1 row_mask:0xf bank_mask:0xf
	v_fmac_f32_dpp v91, v83, v143 row_shr:1 row_mask:0xf bank_mask:0xf
	v_fmac_f32_dpp v88, v80, v132 row_shr:2 row_mask:0xf bank_mask:0xf
	v_fmac_f32_dpp v89, v81, v133 row_shr:2 row_mask:0xf bank_mask:0xf
	v_fmac_f32_dpp v90, v82, v134 row_shr:2 row_mask:0xf bank_mask:0xf
	v_fmac_f32_dpp v91, v83, v135 row_shr:2 row_mask:0xf bank_mask:0xf
	v_fmac_f32_dpp v88, v84, v220 row_ror:1 row_mask:0xf bank_mask:0xf bound_ctrl:1
	v_fmac_f32_dpp v89, v85, v221 row_ror:1 row_mask:0xf bank_mask:0xf bound_ctrl:1
	v_fmac_f32_dpp v90, v86, v222 row_ror:1 row_mask:0xf bank_mask:0xf bound_ctrl:1
	v_fmac_f32_dpp v91, v87, v223 row_ror:1 row_mask:0xf bank_mask:0xf bound_ctrl:1
	v_fmac_f32_dpp v88, v84, v224 row_ror:2 row_mask:0xf bank_mask:0xf bound_ctrl:1
	v_fmac_f32_dpp v89, v85, v225 row_ror:2 row_mask:0xf bank_mask:0xf bound_ctrl:1
	v_fmac_f32_dpp v90, v86, v226 row_ror:2 row_mask:0xf bank_mask:0xf bound_ctrl:1
	v_fmac_f32_dpp v91, v87, v227 row_ror:2 row_mask:0xf bank_mask:0xf bound_ctrl:1
	s_nop 0
	v_pk_fma_f32 v[230:231], v[144:145], v[84:85], v[148:149]
	v_pk_fma_f32 v[232:233], v[146:147], v[86:87], v[150:151]
	s_nop 0
	v_fmac_f32_dpp v230, v84, v140 row_shr:1 row_mask:0xf bank_mask:0xf
	v_fmac_f32_dpp v231, v85, v141 row_shr:1 row_mask:0xf bank_mask:0xf
	v_fmac_f32_dpp v232, v86, v142 row_shr:1 row_mask:0xf bank_mask:0xf
	v_fmac_f32_dpp v233, v87, v143 row_shr:1 row_mask:0xf bank_mask:0xf
	v_fmac_f32_dpp v230, v84, v132 row_shr:2 row_mask:0xf bank_mask:0xf
	v_fmac_f32_dpp v231, v85, v133 row_shr:2 row_mask:0xf bank_mask:0xf
	v_fmac_f32_dpp v232, v86, v134 row_shr:2 row_mask:0xf bank_mask:0xf
	v_fmac_f32_dpp v233, v87, v135 row_shr:2 row_mask:0xf bank_mask:0xf
	v_fmac_f32_dpp v230, v96, v220 row_ror:1 row_mask:0xf bank_mask:0xf bound_ctrl:1
	v_fmac_f32_dpp v231, v97, v221 row_ror:1 row_mask:0xf bank_mask:0xf bound_ctrl:1
	v_fmac_f32_dpp v232, v98, v222 row_ror:1 row_mask:0xf bank_mask:0xf bound_ctrl:1
	v_fmac_f32_dpp v233, v99, v223 row_ror:1 row_mask:0xf bank_mask:0xf bound_ctrl:1
	v_fmac_f32_dpp v230, v96, v224 row_ror:2 row_mask:0xf bank_mask:0xf bound_ctrl:1
	v_fmac_f32_dpp v231, v97, v225 row_ror:2 row_mask:0xf bank_mask:0xf bound_ctrl:1
	v_fmac_f32_dpp v232, v98, v226 row_ror:2 row_mask:0xf bank_mask:0xf bound_ctrl:1
	v_fmac_f32_dpp v233, v99, v227 row_ror:2 row_mask:0xf bank_mask:0xf bound_ctrl:1
	v_mov_b64_e32 v[84:85], v[230:231]
	v_mov_b64_e32 v[86:87], v[232:233]
	s_nop 0
	s_waitcnt lgkmcnt(0)
	v_pk_fma_f32 v[80:81], v[144:145], v[96:97], v[148:149]
	v_pk_fma_f32 v[82:83], v[146:147], v[98:99], v[150:151]
	s_nop 0
	v_fmac_f32_dpp v80, v96, v140 row_shr:1 row_mask:0xf bank_mask:0xf
	v_fmac_f32_dpp v81, v97, v141 row_shr:1 row_mask:0xf bank_mask:0xf
	v_fmac_f32_dpp v82, v98, v142 row_shr:1 row_mask:0xf bank_mask:0xf
	v_fmac_f32_dpp v83, v99, v143 row_shr:1 row_mask:0xf bank_mask:0xf
	v_fmac_f32_dpp v80, v96, v132 row_shr:2 row_mask:0xf bank_mask:0xf
	v_fmac_f32_dpp v81, v97, v133 row_shr:2 row_mask:0xf bank_mask:0xf
	v_fmac_f32_dpp v82, v98, v134 row_shr:2 row_mask:0xf bank_mask:0xf
	v_fmac_f32_dpp v83, v99, v135 row_shr:2 row_mask:0xf bank_mask:0xf
	v_fmac_f32_dpp v80, v136, v220 row_ror:1 row_mask:0xf bank_mask:0xf bound_ctrl:1
	v_fmac_f32_dpp v81, v137, v221 row_ror:1 row_mask:0xf bank_mask:0xf bound_ctrl:1
	v_fmac_f32_dpp v82, v138, v222 row_ror:1 row_mask:0xf bank_mask:0xf bound_ctrl:1
	v_fmac_f32_dpp v83, v139, v223 row_ror:1 row_mask:0xf bank_mask:0xf bound_ctrl:1
	v_fmac_f32_dpp v80, v136, v224 row_ror:2 row_mask:0xf bank_mask:0xf bound_ctrl:1
	v_fmac_f32_dpp v81, v137, v225 row_ror:2 row_mask:0xf bank_mask:0xf bound_ctrl:1
	v_fmac_f32_dpp v82, v138, v226 row_ror:2 row_mask:0xf bank_mask:0xf bound_ctrl:1
	v_fmac_f32_dpp v83, v139, v227 row_ror:2 row_mask:0xf bank_mask:0xf bound_ctrl:1
	s_nop 0
	v_mul_f32_e32 v64, v124, v124
	v_mul_f32_e32 v65, v125, v125
	v_mul_f32_e32 v66, v126, v126
	v_mul_f32_e32 v67, v127, v127
	v_fmamk_f32 v64, v64, 0xbdd2d3e2, v215
	v_fmamk_f32 v65, v65, 0xbdd2d3e2, v215
	v_fmamk_f32 v66, v66, 0xbdd2d3e2, v215
	v_fmamk_f32 v67, v67, 0xbdd2d3e2, v215
	v_mul_f32_e32 v64, v124, v64
	v_mul_f32_e32 v65, v125, v65
	v_mul_f32_e32 v66, v126, v66
	v_mul_f32_e32 v67, v127, v67
	v_exp_f32_e32 v64, v64
	v_exp_f32_e32 v65, v65
	v_exp_f32_e32 v66, v66
	v_exp_f32_e32 v67, v67
	v_add_f32_e32 v64, 1.0, v64
	v_add_f32_e32 v65, 1.0, v65
	v_add_f32_e32 v66, 1.0, v66
	v_add_f32_e32 v67, 1.0, v67
	v_rcp_f32_e32 v64, v64
	v_rcp_f32_e32 v65, v65
	v_rcp_f32_e32 v66, v66
	v_rcp_f32_e32 v67, v67
	v_pk_mul_f32 v[64:65], v[124:125], v[64:65]
	s_nop 0
	v_pk_mul_f32 v[64:65], v[64:65], v[72:73]
	v_pk_mul_f32 v[66:67], v[126:127], v[66:67]
	s_nop 0
	v_pk_mul_f32 v[66:67], v[66:67], v[74:75]
	s_nop 0
	v_mul_f32_e32 v72, v68, v68
	v_mul_f32_e32 v73, v69, v69
	v_mul_f32_e32 v74, v70, v70
	v_mul_f32_e32 v75, v71, v71
	v_fmamk_f32 v72, v72, 0xbdd2d3e2, v215
	v_fmamk_f32 v73, v73, 0xbdd2d3e2, v215
	v_fmamk_f32 v74, v74, 0xbdd2d3e2, v215
	v_fmamk_f32 v75, v75, 0xbdd2d3e2, v215
	v_mul_f32_e32 v72, v68, v72
	v_mul_f32_e32 v73, v69, v73
	v_mul_f32_e32 v74, v70, v74
	v_mul_f32_e32 v75, v71, v75
	v_exp_f32_e32 v72, v72
	v_exp_f32_e32 v73, v73
	v_exp_f32_e32 v74, v74
	v_exp_f32_e32 v75, v75
	v_add_f32_e32 v72, 1.0, v72
	v_add_f32_e32 v73, 1.0, v73
	v_add_f32_e32 v74, 1.0, v74
	v_add_f32_e32 v75, 1.0, v75
	v_rcp_f32_e32 v72, v72
	v_rcp_f32_e32 v73, v73
	v_rcp_f32_e32 v74, v74
	v_rcp_f32_e32 v75, v75
	v_pk_mul_f32 v[68:69], v[68:69], v[72:73]
	s_nop 0
	v_pk_mul_f32 v[68:69], v[68:69], v[152:153]
	v_pk_mul_f32 v[70:71], v[70:71], v[74:75]
	s_nop 0
	v_pk_mul_f32 v[70:71], v[70:71], v[154:155]
	s_nop 0
	v_mul_f32_e32 v72, v100, v100
	v_mul_f32_e32 v73, v101, v101
	v_mul_f32_e32 v74, v102, v102
	v_mul_f32_e32 v75, v103, v103
	v_fmamk_f32 v72, v72, 0xbdd2d3e2, v215
	v_fmamk_f32 v73, v73, 0xbdd2d3e2, v215
	v_fmamk_f32 v74, v74, 0xbdd2d3e2, v215
	v_fmamk_f32 v75, v75, 0xbdd2d3e2, v215
	v_mul_f32_e32 v72, v100, v72
	v_mul_f32_e32 v73, v101, v73
	v_mul_f32_e32 v74, v102, v74
	v_mul_f32_e32 v75, v103, v75
	v_exp_f32_e32 v72, v72
	v_exp_f32_e32 v73, v73
	v_exp_f32_e32 v74, v74
	v_exp_f32_e32 v75, v75
	v_add_f32_e32 v72, 1.0, v72
	v_add_f32_e32 v73, 1.0, v73
	v_add_f32_e32 v74, 1.0, v74
	v_add_f32_e32 v75, 1.0, v75
	v_rcp_f32_e32 v72, v72
	v_rcp_f32_e32 v73, v73
	v_rcp_f32_e32 v74, v74
	v_rcp_f32_e32 v75, v75
	v_pk_mul_f32 v[72:73], v[100:101], v[72:73]
	s_nop 0
	v_pk_mul_f32 v[72:73], v[72:73], v[128:129]
	v_pk_mul_f32 v[74:75], v[102:103], v[74:75]
	s_nop 0
	v_pk_mul_f32 v[74:75], v[74:75], v[130:131]
	s_nop 0
	v_mul_f32_e32 v96, v76, v76
	v_mul_f32_e32 v97, v77, v77
	v_mul_f32_e32 v98, v78, v78
	v_mul_f32_e32 v99, v79, v79
	v_fmamk_f32 v96, v96, 0xbdd2d3e2, v215
	v_fmamk_f32 v97, v97, 0xbdd2d3e2, v215
	v_fmamk_f32 v98, v98, 0xbdd2d3e2, v215
	v_fmamk_f32 v99, v99, 0xbdd2d3e2, v215
	v_mul_f32_e32 v96, v76, v96
	v_mul_f32_e32 v97, v77, v97
	v_mul_f32_e32 v98, v78, v98
	v_mul_f32_e32 v99, v79, v99
	v_exp_f32_e32 v96, v96
	v_exp_f32_e32 v97, v97
	v_exp_f32_e32 v98, v98
	v_exp_f32_e32 v99, v99
	v_add_f32_e32 v96, 1.0, v96
	v_add_f32_e32 v97, 1.0, v97
	v_add_f32_e32 v98, 1.0, v98
	v_add_f32_e32 v99, 1.0, v99
	v_rcp_f32_e32 v96, v96
	v_rcp_f32_e32 v97, v97
	v_rcp_f32_e32 v98, v98
	v_rcp_f32_e32 v99, v99
	v_pk_mul_f32 v[76:77], v[76:77], v[96:97]
	s_nop 0
	v_pk_mul_f32 v[76:77], v[76:77], v[108:109]
	v_pk_mul_f32 v[78:79], v[78:79], v[98:99]
	s_nop 0
	v_pk_mul_f32 v[78:79], v[78:79], v[110:111]
	s_nop 0
	v_mul_f32_e32 v96, v120, v120
	v_mul_f32_e32 v97, v121, v121
	v_mul_f32_e32 v98, v122, v122
	v_mul_f32_e32 v99, v123, v123
	v_fmamk_f32 v96, v96, 0xbdd2d3e2, v215
	v_fmamk_f32 v97, v97, 0xbdd2d3e2, v215
	v_fmamk_f32 v98, v98, 0xbdd2d3e2, v215
	v_fmamk_f32 v99, v99, 0xbdd2d3e2, v215
	v_mul_f32_e32 v96, v120, v96
	v_mul_f32_e32 v97, v121, v97
	v_mul_f32_e32 v98, v122, v98
	v_mul_f32_e32 v99, v123, v99
	v_exp_f32_e32 v96, v96
	v_exp_f32_e32 v97, v97
	v_exp_f32_e32 v98, v98
	v_exp_f32_e32 v99, v99
	v_add_f32_e32 v96, 1.0, v96
	v_add_f32_e32 v97, 1.0, v97
	v_add_f32_e32 v98, 1.0, v98
	v_add_f32_e32 v99, 1.0, v99
	v_rcp_f32_e32 v96, v96
	v_rcp_f32_e32 v97, v97
	v_rcp_f32_e32 v98, v98
	v_rcp_f32_e32 v99, v99
	v_pk_mul_f32 v[96:97], v[120:121], v[96:97]
	s_nop 0
	v_pk_mul_f32 v[80:81], v[96:97], v[80:81]
	v_pk_mul_f32 v[98:99], v[122:123], v[98:99]
	s_nop 0
	v_pk_mul_f32 v[82:83], v[98:99], v[82:83]
	s_nop 0
	v_mul_f32_e32 v96, v116, v116
	v_mul_f32_e32 v97, v117, v117
	v_mul_f32_e32 v98, v118, v118
	v_mul_f32_e32 v99, v119, v119
	v_fmamk_f32 v96, v96, 0xbdd2d3e2, v215
	v_fmamk_f32 v97, v97, 0xbdd2d3e2, v215
	v_fmamk_f32 v98, v98, 0xbdd2d3e2, v215
	v_fmamk_f32 v99, v99, 0xbdd2d3e2, v215
	v_mul_f32_e32 v96, v116, v96
	v_mul_f32_e32 v97, v117, v97
	v_mul_f32_e32 v98, v118, v98
	v_mul_f32_e32 v99, v119, v99
	v_exp_f32_e32 v96, v96
	v_exp_f32_e32 v97, v97
	v_exp_f32_e32 v98, v98
	v_exp_f32_e32 v99, v99
	v_add_f32_e32 v96, 1.0, v96
	v_add_f32_e32 v97, 1.0, v97
	v_add_f32_e32 v98, 1.0, v98
	v_add_f32_e32 v99, 1.0, v99
	v_rcp_f32_e32 v96, v96
	v_rcp_f32_e32 v97, v97
	v_rcp_f32_e32 v98, v98
	v_rcp_f32_e32 v99, v99
	v_pk_mul_f32 v[96:97], v[116:117], v[96:97]
	s_nop 0
	v_pk_mul_f32 v[84:85], v[96:97], v[84:85]
	v_pk_mul_f32 v[98:99], v[118:119], v[98:99]
	s_nop 0
	v_pk_mul_f32 v[86:87], v[98:99], v[86:87]
	s_nop 0
	v_mul_f32_e32 v96, v112, v112
	v_mul_f32_e32 v97, v113, v113
	v_mul_f32_e32 v98, v114, v114
	v_mul_f32_e32 v99, v115, v115
	v_fmamk_f32 v96, v96, 0xbdd2d3e2, v215
	v_fmamk_f32 v97, v97, 0xbdd2d3e2, v215
	v_fmamk_f32 v98, v98, 0xbdd2d3e2, v215
	v_fmamk_f32 v99, v99, 0xbdd2d3e2, v215
	v_mul_f32_e32 v96, v112, v96
	v_mul_f32_e32 v97, v113, v97
	v_mul_f32_e32 v98, v114, v98
	v_mul_f32_e32 v99, v115, v99
	v_exp_f32_e32 v96, v96
	v_exp_f32_e32 v97, v97
	v_exp_f32_e32 v98, v98
	v_exp_f32_e32 v99, v99
	v_add_f32_e32 v96, 1.0, v96
	v_add_f32_e32 v97, 1.0, v97
	v_add_f32_e32 v98, 1.0, v98
	v_add_f32_e32 v99, 1.0, v99
	v_rcp_f32_e32 v96, v96
	v_rcp_f32_e32 v97, v97
	v_rcp_f32_e32 v98, v98
	v_rcp_f32_e32 v99, v99
	v_pk_mul_f32 v[96:97], v[112:113], v[96:97]
	s_nop 0
	v_pk_mul_f32 v[88:89], v[96:97], v[88:89]
	v_pk_mul_f32 v[98:99], v[114:115], v[98:99]
	s_nop 0
	v_pk_mul_f32 v[90:91], v[98:99], v[90:91]
	s_nop 0
	v_mul_f32_e32 v96, v92, v92
	v_mul_f32_e32 v97, v93, v93
	v_mul_f32_e32 v98, v94, v94
	v_mul_f32_e32 v99, v95, v95
	v_fmamk_f32 v96, v96, 0xbdd2d3e2, v215
	v_fmamk_f32 v97, v97, 0xbdd2d3e2, v215
	v_fmamk_f32 v98, v98, 0xbdd2d3e2, v215
	v_fmamk_f32 v99, v99, 0xbdd2d3e2, v215
	v_mul_f32_e32 v96, v92, v96
	v_mul_f32_e32 v97, v93, v97
	v_mul_f32_e32 v98, v94, v98
	v_mul_f32_e32 v99, v95, v99
	v_exp_f32_e32 v96, v96
	v_exp_f32_e32 v97, v97
	v_exp_f32_e32 v98, v98
	v_exp_f32_e32 v99, v99
	v_add_f32_e32 v96, 1.0, v96
	v_add_f32_e32 v97, 1.0, v97
	v_add_f32_e32 v98, 1.0, v98
	v_add_f32_e32 v99, 1.0, v99
	v_rcp_f32_e32 v96, v96
	v_rcp_f32_e32 v97, v97
	v_rcp_f32_e32 v98, v98
	v_rcp_f32_e32 v99, v99
	v_pk_mul_f32 v[92:93], v[92:93], v[96:97]
	s_nop 0
	v_pk_mul_f32 v[92:93], v[92:93], v[104:105]
	v_pk_mul_f32 v[94:95], v[94:95], v[98:99]
	s_nop 0
	v_pk_mul_f32 v[94:95], v[94:95], v[106:107]
	s_nop 0
	v_or_b32_e32 v96, 4, v204
	v_ashrrev_i32_e32 v97, 31, v96
	v_lshlrev_b64 v[96:97], 2, v[96:97]
	v_lshl_add_u64 v[98:99], s[36:37], 0, v[96:97]
	global_load_dwordx4 v[114:117], v[206:207], off offset:16
	v_lshl_add_u64 v[96:97], s[38:39], 0, v[96:97]
	global_load_dwordx4 v[110:113], v[98:99], off
	global_load_dwordx4 v[106:109], v[96:97], off
	global_load_dwordx4 v[118:121], v[208:209], off offset:16
	v_mov_b32_e32 v104, 0
	s_and_b64 vcc, exec, s[8:9]
	v_mov_b32_e32 v100, 0
	v_mov_b32_e32 v101, 0
	v_mov_b32_e32 v102, 0
	v_mov_b32_e32 v103, 0
	s_cbranch_vccnz .LBB0_995
	ds_read_b128 v[100:103], v212 offset:16
.LBB0_995:
	s_waitcnt vmcnt(0)
	v_cndmask_b32_e64 v220, 0, v110, s[98:99]
	v_cndmask_b32_e64 v224, 0, v106, s[100:101]
	v_cndmask_b32_e64 v221, 0, v111, s[98:99]
	v_cndmask_b32_e64 v225, 0, v107, s[100:101]
	v_cndmask_b32_e64 v222, 0, v112, s[98:99]
	v_cndmask_b32_e64 v226, 0, v108, s[100:101]
	v_cndmask_b32_e64 v223, 0, v113, s[98:99]
	v_cndmask_b32_e64 v227, 0, v109, s[100:101]
	v_pk_fma_f32 v[230:231], v[114:115], v[52:53], v[118:119]
	v_pk_fma_f32 v[232:233], v[116:117], v[54:55], v[120:121]
	s_nop 0
	v_fmac_f32_dpp v230, v52, v110 row_shr:1 row_mask:0xf bank_mask:0xf
	v_fmac_f32_dpp v231, v53, v111 row_shr:1 row_mask:0xf bank_mask:0xf
	v_fmac_f32_dpp v232, v54, v112 row_shr:1 row_mask:0xf bank_mask:0xf
	v_fmac_f32_dpp v233, v55, v113 row_shr:1 row_mask:0xf bank_mask:0xf
	v_fmac_f32_dpp v230, v52, v106 row_shr:2 row_mask:0xf bank_mask:0xf
	v_fmac_f32_dpp v231, v53, v107 row_shr:2 row_mask:0xf bank_mask:0xf
	v_fmac_f32_dpp v232, v54, v108 row_shr:2 row_mask:0xf bank_mask:0xf
	v_fmac_f32_dpp v233, v55, v109 row_shr:2 row_mask:0xf bank_mask:0xf
	v_fmac_f32_dpp v230, v44, v220 row_ror:1 row_mask:0xf bank_mask:0xf bound_ctrl:1
	v_fmac_f32_dpp v231, v45, v221 row_ror:1 row_mask:0xf bank_mask:0xf bound_ctrl:1
	v_fmac_f32_dpp v232, v46, v222 row_ror:1 row_mask:0xf bank_mask:0xf bound_ctrl:1
	v_fmac_f32_dpp v233, v47, v223 row_ror:1 row_mask:0xf bank_mask:0xf bound_ctrl:1
	v_fmac_f32_dpp v230, v44, v224 row_ror:2 row_mask:0xf bank_mask:0xf bound_ctrl:1
	v_fmac_f32_dpp v231, v45, v225 row_ror:2 row_mask:0xf bank_mask:0xf bound_ctrl:1
	v_fmac_f32_dpp v232, v46, v226 row_ror:2 row_mask:0xf bank_mask:0xf bound_ctrl:1
	v_fmac_f32_dpp v233, v47, v227 row_ror:2 row_mask:0xf bank_mask:0xf bound_ctrl:1
	v_mov_b64_e32 v[52:53], v[230:231]
	v_mov_b64_e32 v[54:55], v[232:233]
	s_nop 0
	v_pk_fma_f32 v[230:231], v[114:115], v[44:45], v[118:119]
	v_pk_fma_f32 v[232:233], v[116:117], v[46:47], v[120:121]
	s_nop 0
	v_fmac_f32_dpp v230, v44, v110 row_shr:1 row_mask:0xf bank_mask:0xf
	v_fmac_f32_dpp v231, v45, v111 row_shr:1 row_mask:0xf bank_mask:0xf
	v_fmac_f32_dpp v232, v46, v112 row_shr:1 row_mask:0xf bank_mask:0xf
	v_fmac_f32_dpp v233, v47, v113 row_shr:1 row_mask:0xf bank_mask:0xf
	v_fmac_f32_dpp v230, v44, v106 row_shr:2 row_mask:0xf bank_mask:0xf
	v_fmac_f32_dpp v231, v45, v107 row_shr:2 row_mask:0xf bank_mask:0xf
	v_fmac_f32_dpp v232, v46, v108 row_shr:2 row_mask:0xf bank_mask:0xf
	v_fmac_f32_dpp v233, v47, v109 row_shr:2 row_mask:0xf bank_mask:0xf
	v_fmac_f32_dpp v230, v32, v220 row_ror:1 row_mask:0xf bank_mask:0xf bound_ctrl:1
	v_fmac_f32_dpp v231, v33, v221 row_ror:1 row_mask:0xf bank_mask:0xf bound_ctrl:1
	v_fmac_f32_dpp v232, v34, v222 row_ror:1 row_mask:0xf bank_mask:0xf bound_ctrl:1
	v_fmac_f32_dpp v233, v35, v223 row_ror:1 row_mask:0xf bank_mask:0xf bound_ctrl:1
	v_fmac_f32_dpp v230, v32, v224 row_ror:2 row_mask:0xf bank_mask:0xf bound_ctrl:1
	v_fmac_f32_dpp v231, v33, v225 row_ror:2 row_mask:0xf bank_mask:0xf bound_ctrl:1
	v_fmac_f32_dpp v232, v34, v226 row_ror:2 row_mask:0xf bank_mask:0xf bound_ctrl:1
	v_fmac_f32_dpp v233, v35, v227 row_ror:2 row_mask:0xf bank_mask:0xf bound_ctrl:1
	v_mov_b64_e32 v[44:45], v[230:231]
	v_mov_b64_e32 v[46:47], v[232:233]
	s_nop 0
	v_pk_fma_f32 v[96:97], v[114:115], v[32:33], v[118:119]
	v_pk_fma_f32 v[98:99], v[116:117], v[34:35], v[120:121]
	s_nop 0
	v_fmac_f32_dpp v96, v32, v110 row_shr:1 row_mask:0xf bank_mask:0xf
	v_fmac_f32_dpp v97, v33, v111 row_shr:1 row_mask:0xf bank_mask:0xf
	v_fmac_f32_dpp v98, v34, v112 row_shr:1 row_mask:0xf bank_mask:0xf
	v_fmac_f32_dpp v99, v35, v113 row_shr:1 row_mask:0xf bank_mask:0xf
	v_fmac_f32_dpp v96, v32, v106 row_shr:2 row_mask:0xf bank_mask:0xf
	v_fmac_f32_dpp v97, v33, v107 row_shr:2 row_mask:0xf bank_mask:0xf
	v_fmac_f32_dpp v98, v34, v108 row_shr:2 row_mask:0xf bank_mask:0xf
	v_fmac_f32_dpp v99, v35, v109 row_shr:2 row_mask:0xf bank_mask:0xf
	v_fmac_f32_dpp v96, v24, v220 row_ror:1 row_mask:0xf bank_mask:0xf bound_ctrl:1
	v_fmac_f32_dpp v97, v25, v221 row_ror:1 row_mask:0xf bank_mask:0xf bound_ctrl:1
	v_fmac_f32_dpp v98, v26, v222 row_ror:1 row_mask:0xf bank_mask:0xf bound_ctrl:1
	v_fmac_f32_dpp v99, v27, v223 row_ror:1 row_mask:0xf bank_mask:0xf bound_ctrl:1
	v_fmac_f32_dpp v96, v24, v224 row_ror:2 row_mask:0xf bank_mask:0xf bound_ctrl:1
	v_fmac_f32_dpp v97, v25, v225 row_ror:2 row_mask:0xf bank_mask:0xf bound_ctrl:1
	v_fmac_f32_dpp v98, v26, v226 row_ror:2 row_mask:0xf bank_mask:0xf bound_ctrl:1
	v_fmac_f32_dpp v99, v27, v227 row_ror:2 row_mask:0xf bank_mask:0xf bound_ctrl:1
	s_nop 0
	s_waitcnt lgkmcnt(0)
	v_pk_fma_f32 v[230:231], v[114:115], v[24:25], v[118:119]
	v_pk_fma_f32 v[232:233], v[116:117], v[26:27], v[120:121]
	s_nop 0
	v_fmac_f32_dpp v230, v24, v110 row_shr:1 row_mask:0xf bank_mask:0xf
	v_fmac_f32_dpp v231, v25, v111 row_shr:1 row_mask:0xf bank_mask:0xf
	v_fmac_f32_dpp v232, v26, v112 row_shr:1 row_mask:0xf bank_mask:0xf
	v_fmac_f32_dpp v233, v27, v113 row_shr:1 row_mask:0xf bank_mask:0xf
	v_fmac_f32_dpp v230, v24, v106 row_shr:2 row_mask:0xf bank_mask:0xf
	v_fmac_f32_dpp v231, v25, v107 row_shr:2 row_mask:0xf bank_mask:0xf
	v_fmac_f32_dpp v232, v26, v108 row_shr:2 row_mask:0xf bank_mask:0xf
	v_fmac_f32_dpp v233, v27, v109 row_shr:2 row_mask:0xf bank_mask:0xf
	v_fmac_f32_dpp v230, v100, v220 row_ror:1 row_mask:0xf bank_mask:0xf bound_ctrl:1
	v_fmac_f32_dpp v231, v101, v221 row_ror:1 row_mask:0xf bank_mask:0xf bound_ctrl:1
	v_fmac_f32_dpp v232, v102, v222 row_ror:1 row_mask:0xf bank_mask:0xf bound_ctrl:1
	v_fmac_f32_dpp v233, v103, v223 row_ror:1 row_mask:0xf bank_mask:0xf bound_ctrl:1
	v_fmac_f32_dpp v230, v100, v224 row_ror:2 row_mask:0xf bank_mask:0xf bound_ctrl:1
	v_fmac_f32_dpp v231, v101, v225 row_ror:2 row_mask:0xf bank_mask:0xf bound_ctrl:1
	v_fmac_f32_dpp v232, v102, v226 row_ror:2 row_mask:0xf bank_mask:0xf bound_ctrl:1
	v_fmac_f32_dpp v233, v103, v227 row_ror:2 row_mask:0xf bank_mask:0xf bound_ctrl:1
	v_mov_b64_e32 v[100:101], v[230:231]
	v_mov_b64_e32 v[102:103], v[232:233]
	s_nop 0
	ds_read_b128 v[122:125], v212 offset:4112
	v_pk_fma_f32 v[24:25], v[114:115], v[60:61], v[118:119]
	v_pk_fma_f32 v[26:27], v[116:117], v[62:63], v[120:121]
	s_nop 0
	v_fmac_f32_dpp v24, v60, v110 row_shr:1 row_mask:0xf bank_mask:0xf
	v_fmac_f32_dpp v25, v61, v111 row_shr:1 row_mask:0xf bank_mask:0xf
	v_fmac_f32_dpp v26, v62, v112 row_shr:1 row_mask:0xf bank_mask:0xf
	v_fmac_f32_dpp v27, v63, v113 row_shr:1 row_mask:0xf bank_mask:0xf
	v_fmac_f32_dpp v24, v60, v106 row_shr:2 row_mask:0xf bank_mask:0xf
	v_fmac_f32_dpp v25, v61, v107 row_shr:2 row_mask:0xf bank_mask:0xf
	v_fmac_f32_dpp v26, v62, v108 row_shr:2 row_mask:0xf bank_mask:0xf
	v_fmac_f32_dpp v27, v63, v109 row_shr:2 row_mask:0xf bank_mask:0xf
	v_fmac_f32_dpp v24, v56, v220 row_ror:1 row_mask:0xf bank_mask:0xf bound_ctrl:1
	v_fmac_f32_dpp v25, v57, v221 row_ror:1 row_mask:0xf bank_mask:0xf bound_ctrl:1
	v_fmac_f32_dpp v26, v58, v222 row_ror:1 row_mask:0xf bank_mask:0xf bound_ctrl:1
	v_fmac_f32_dpp v27, v59, v223 row_ror:1 row_mask:0xf bank_mask:0xf bound_ctrl:1
	v_fmac_f32_dpp v24, v56, v224 row_ror:2 row_mask:0xf bank_mask:0xf bound_ctrl:1
	v_fmac_f32_dpp v25, v57, v225 row_ror:2 row_mask:0xf bank_mask:0xf bound_ctrl:1
	v_fmac_f32_dpp v26, v58, v226 row_ror:2 row_mask:0xf bank_mask:0xf bound_ctrl:1
	v_fmac_f32_dpp v27, v59, v227 row_ror:2 row_mask:0xf bank_mask:0xf bound_ctrl:1
	s_nop 0
	v_pk_fma_f32 v[32:33], v[114:115], v[56:57], v[118:119]
	v_pk_fma_f32 v[34:35], v[116:117], v[58:59], v[120:121]
	s_nop 0
	v_fmac_f32_dpp v32, v56, v110 row_shr:1 row_mask:0xf bank_mask:0xf
	v_fmac_f32_dpp v33, v57, v111 row_shr:1 row_mask:0xf bank_mask:0xf
	v_fmac_f32_dpp v34, v58, v112 row_shr:1 row_mask:0xf bank_mask:0xf
	v_fmac_f32_dpp v35, v59, v113 row_shr:1 row_mask:0xf bank_mask:0xf
	v_fmac_f32_dpp v32, v56, v106 row_shr:2 row_mask:0xf bank_mask:0xf
	v_fmac_f32_dpp v33, v57, v107 row_shr:2 row_mask:0xf bank_mask:0xf
	v_fmac_f32_dpp v34, v58, v108 row_shr:2 row_mask:0xf bank_mask:0xf
	v_fmac_f32_dpp v35, v59, v109 row_shr:2 row_mask:0xf bank_mask:0xf
	v_fmac_f32_dpp v32, v48, v220 row_ror:1 row_mask:0xf bank_mask:0xf bound_ctrl:1
	v_fmac_f32_dpp v33, v49, v221 row_ror:1 row_mask:0xf bank_mask:0xf bound_ctrl:1
	v_fmac_f32_dpp v34, v50, v222 row_ror:1 row_mask:0xf bank_mask:0xf bound_ctrl:1
	v_fmac_f32_dpp v35, v51, v223 row_ror:1 row_mask:0xf bank_mask:0xf bound_ctrl:1
	v_fmac_f32_dpp v32, v48, v224 row_ror:2 row_mask:0xf bank_mask:0xf bound_ctrl:1
	v_fmac_f32_dpp v33, v49, v225 row_ror:2 row_mask:0xf bank_mask:0xf bound_ctrl:1
	v_fmac_f32_dpp v34, v50, v226 row_ror:2 row_mask:0xf bank_mask:0xf bound_ctrl:1
	v_fmac_f32_dpp v35, v51, v227 row_ror:2 row_mask:0xf bank_mask:0xf bound_ctrl:1
	s_nop 0
	v_pk_fma_f32 v[230:231], v[114:115], v[48:49], v[118:119]
	v_pk_fma_f32 v[232:233], v[116:117], v[50:51], v[120:121]
	s_nop 0
	v_fmac_f32_dpp v230, v48, v110 row_shr:1 row_mask:0xf bank_mask:0xf
	v_fmac_f32_dpp v231, v49, v111 row_shr:1 row_mask:0xf bank_mask:0xf
	v_fmac_f32_dpp v232, v50, v112 row_shr:1 row_mask:0xf bank_mask:0xf
	v_fmac_f32_dpp v233, v51, v113 row_shr:1 row_mask:0xf bank_mask:0xf
	v_fmac_f32_dpp v230, v48, v106 row_shr:2 row_mask:0xf bank_mask:0xf
	v_fmac_f32_dpp v231, v49, v107 row_shr:2 row_mask:0xf bank_mask:0xf
	v_fmac_f32_dpp v232, v50, v108 row_shr:2 row_mask:0xf bank_mask:0xf
	v_fmac_f32_dpp v233, v51, v109 row_shr:2 row_mask:0xf bank_mask:0xf
	v_fmac_f32_dpp v230, v40, v220 row_ror:1 row_mask:0xf bank_mask:0xf bound_ctrl:1
	v_fmac_f32_dpp v231, v41, v221 row_ror:1 row_mask:0xf bank_mask:0xf bound_ctrl:1
	v_fmac_f32_dpp v232, v42, v222 row_ror:1 row_mask:0xf bank_mask:0xf bound_ctrl:1
	v_fmac_f32_dpp v233, v43, v223 row_ror:1 row_mask:0xf bank_mask:0xf bound_ctrl:1
	v_fmac_f32_dpp v230, v40, v224 row_ror:2 row_mask:0xf bank_mask:0xf bound_ctrl:1
	v_fmac_f32_dpp v231, v41, v225 row_ror:2 row_mask:0xf bank_mask:0xf bound_ctrl:1
	v_fmac_f32_dpp v232, v42, v226 row_ror:2 row_mask:0xf bank_mask:0xf bound_ctrl:1
	v_fmac_f32_dpp v233, v43, v227 row_ror:2 row_mask:0xf bank_mask:0xf bound_ctrl:1
	v_mov_b64_e32 v[48:49], v[230:231]
	v_mov_b64_e32 v[50:51], v[232:233]
	s_nop 0
	s_waitcnt lgkmcnt(0)
	v_pk_fma_f32 v[230:231], v[114:115], v[40:41], v[118:119]
	v_pk_fma_f32 v[232:233], v[116:117], v[42:43], v[120:121]
	s_nop 0
	v_fmac_f32_dpp v230, v40, v110 row_shr:1 row_mask:0xf bank_mask:0xf
	v_fmac_f32_dpp v231, v41, v111 row_shr:1 row_mask:0xf bank_mask:0xf
	v_fmac_f32_dpp v232, v42, v112 row_shr:1 row_mask:0xf bank_mask:0xf
	v_fmac_f32_dpp v233, v43, v113 row_shr:1 row_mask:0xf bank_mask:0xf
	v_fmac_f32_dpp v230, v40, v106 row_shr:2 row_mask:0xf bank_mask:0xf
	v_fmac_f32_dpp v231, v41, v107 row_shr:2 row_mask:0xf bank_mask:0xf
	v_fmac_f32_dpp v232, v42, v108 row_shr:2 row_mask:0xf bank_mask:0xf
	v_fmac_f32_dpp v233, v43, v109 row_shr:2 row_mask:0xf bank_mask:0xf
	v_fmac_f32_dpp v230, v122, v220 row_ror:1 row_mask:0xf bank_mask:0xf bound_ctrl:1
	v_fmac_f32_dpp v231, v123, v221 row_ror:1 row_mask:0xf bank_mask:0xf bound_ctrl:1
	v_fmac_f32_dpp v232, v124, v222 row_ror:1 row_mask:0xf bank_mask:0xf bound_ctrl:1
	v_fmac_f32_dpp v233, v125, v223 row_ror:1 row_mask:0xf bank_mask:0xf bound_ctrl:1
	v_fmac_f32_dpp v230, v122, v224 row_ror:2 row_mask:0xf bank_mask:0xf bound_ctrl:1
	v_fmac_f32_dpp v231, v123, v225 row_ror:2 row_mask:0xf bank_mask:0xf bound_ctrl:1
	v_fmac_f32_dpp v232, v124, v226 row_ror:2 row_mask:0xf bank_mask:0xf bound_ctrl:1
	v_fmac_f32_dpp v233, v125, v227 row_ror:2 row_mask:0xf bank_mask:0xf bound_ctrl:1
	v_mov_b64_e32 v[40:41], v[230:231]
	v_mov_b64_e32 v[42:43], v[232:233]
	s_nop 0
	v_add_u32_e32 v56, 0xc04, v204
	v_ashrrev_i32_e32 v57, 31, v56
	v_lshlrev_b64 v[106:107], 2, v[56:57]
	v_lshl_add_u64 v[56:57], s[24:25], 0, v[106:107]
	v_lshl_add_u64 v[58:59], s[36:37], 0, v[106:107]
	global_load_dwordx4 v[108:111], v[56:57], off
	global_load_dwordx4 v[60:63], v[58:59], off
	v_lshl_add_u64 v[56:57], s[38:39], 0, v[106:107]
	v_lshl_add_u64 v[106:107], s[26:27], 0, v[106:107]
	global_load_dwordx4 v[56:59], v[56:57], off
	s_and_b64 vcc, exec, s[8:9]
	global_load_dwordx4 v[112:115], v[106:107], off
	v_mov_b32_e32 v105, 0
	v_mov_b32_e32 v106, 0
	v_mov_b32_e32 v107, 0
	s_cbranch_vccnz .LBB0_997
	ds_read_b128 v[104:107], v212 offset:528
.LBB0_997:
	s_waitcnt vmcnt(0)
	v_cndmask_b32_e64 v220, 0, v60, s[98:99]
	v_cndmask_b32_e64 v224, 0, v56, s[100:101]
	v_cndmask_b32_e64 v221, 0, v61, s[98:99]
	v_cndmask_b32_e64 v225, 0, v57, s[100:101]
	v_cndmask_b32_e64 v222, 0, v62, s[98:99]
	v_cndmask_b32_e64 v226, 0, v58, s[100:101]
	v_cndmask_b32_e64 v223, 0, v63, s[98:99]
	v_cndmask_b32_e64 v227, 0, v59, s[100:101]
	v_pk_fma_f32 v[230:231], v[108:109], v[20:21], v[112:113]
	v_pk_fma_f32 v[232:233], v[110:111], v[22:23], v[114:115]
	s_nop 0
	v_fmac_f32_dpp v230, v20, v60 row_shr:1 row_mask:0xf bank_mask:0xf
	v_fmac_f32_dpp v231, v21, v61 row_shr:1 row_mask:0xf bank_mask:0xf
	v_fmac_f32_dpp v232, v22, v62 row_shr:1 row_mask:0xf bank_mask:0xf
	v_fmac_f32_dpp v233, v23, v63 row_shr:1 row_mask:0xf bank_mask:0xf
	v_fmac_f32_dpp v230, v20, v56 row_shr:2 row_mask:0xf bank_mask:0xf
	v_fmac_f32_dpp v231, v21, v57 row_shr:2 row_mask:0xf bank_mask:0xf
	v_fmac_f32_dpp v232, v22, v58 row_shr:2 row_mask:0xf bank_mask:0xf
	v_fmac_f32_dpp v233, v23, v59 row_shr:2 row_mask:0xf bank_mask:0xf
	v_fmac_f32_dpp v230, v12, v220 row_ror:1 row_mask:0xf bank_mask:0xf bound_ctrl:1
	v_fmac_f32_dpp v231, v13, v221 row_ror:1 row_mask:0xf bank_mask:0xf bound_ctrl:1
	v_fmac_f32_dpp v232, v14, v222 row_ror:1 row_mask:0xf bank_mask:0xf bound_ctrl:1
	v_fmac_f32_dpp v233, v15, v223 row_ror:1 row_mask:0xf bank_mask:0xf bound_ctrl:1
	v_fmac_f32_dpp v230, v12, v224 row_ror:2 row_mask:0xf bank_mask:0xf bound_ctrl:1
	v_fmac_f32_dpp v231, v13, v225 row_ror:2 row_mask:0xf bank_mask:0xf bound_ctrl:1
	v_fmac_f32_dpp v232, v14, v226 row_ror:2 row_mask:0xf bank_mask:0xf bound_ctrl:1
	v_fmac_f32_dpp v233, v15, v227 row_ror:2 row_mask:0xf bank_mask:0xf bound_ctrl:1
	v_mov_b64_e32 v[20:21], v[230:231]
	v_mov_b64_e32 v[22:23], v[232:233]
	s_nop 0
	v_pk_fma_f32 v[230:231], v[108:109], v[12:13], v[112:113]
	v_pk_fma_f32 v[232:233], v[110:111], v[14:15], v[114:115]
	s_nop 0
	v_fmac_f32_dpp v230, v12, v60 row_shr:1 row_mask:0xf bank_mask:0xf
	v_fmac_f32_dpp v231, v13, v61 row_shr:1 row_mask:0xf bank_mask:0xf
	v_fmac_f32_dpp v232, v14, v62 row_shr:1 row_mask:0xf bank_mask:0xf
	v_fmac_f32_dpp v233, v15, v63 row_shr:1 row_mask:0xf bank_mask:0xf
	v_fmac_f32_dpp v230, v12, v56 row_shr:2 row_mask:0xf bank_mask:0xf
	v_fmac_f32_dpp v231, v13, v57 row_shr:2 row_mask:0xf bank_mask:0xf
	v_fmac_f32_dpp v232, v14, v58 row_shr:2 row_mask:0xf bank_mask:0xf
	v_fmac_f32_dpp v233, v15, v59 row_shr:2 row_mask:0xf bank_mask:0xf
	v_fmac_f32_dpp v230, v4, v220 row_ror:1 row_mask:0xf bank_mask:0xf bound_ctrl:1
	v_fmac_f32_dpp v231, v5, v221 row_ror:1 row_mask:0xf bank_mask:0xf bound_ctrl:1
	v_fmac_f32_dpp v232, v6, v222 row_ror:1 row_mask:0xf bank_mask:0xf bound_ctrl:1
	v_fmac_f32_dpp v233, v7, v223 row_ror:1 row_mask:0xf bank_mask:0xf bound_ctrl:1
	v_fmac_f32_dpp v230, v4, v224 row_ror:2 row_mask:0xf bank_mask:0xf bound_ctrl:1
	v_fmac_f32_dpp v231, v5, v225 row_ror:2 row_mask:0xf bank_mask:0xf bound_ctrl:1
	v_fmac_f32_dpp v232, v6, v226 row_ror:2 row_mask:0xf bank_mask:0xf bound_ctrl:1
	v_fmac_f32_dpp v233, v7, v227 row_ror:2 row_mask:0xf bank_mask:0xf bound_ctrl:1
	v_mov_b64_e32 v[12:13], v[230:231]
	v_mov_b64_e32 v[14:15], v[232:233]
	s_nop 0
	v_pk_fma_f32 v[116:117], v[108:109], v[4:5], v[112:113]
	v_pk_fma_f32 v[118:119], v[110:111], v[6:7], v[114:115]
	s_nop 0
	v_fmac_f32_dpp v116, v4, v60 row_shr:1 row_mask:0xf bank_mask:0xf
	v_fmac_f32_dpp v117, v5, v61 row_shr:1 row_mask:0xf bank_mask:0xf
	v_fmac_f32_dpp v118, v6, v62 row_shr:1 row_mask:0xf bank_mask:0xf
	v_fmac_f32_dpp v119, v7, v63 row_shr:1 row_mask:0xf bank_mask:0xf
	v_fmac_f32_dpp v116, v4, v56 row_shr:2 row_mask:0xf bank_mask:0xf
	v_fmac_f32_dpp v117, v5, v57 row_shr:2 row_mask:0xf bank_mask:0xf
	v_fmac_f32_dpp v118, v6, v58 row_shr:2 row_mask:0xf bank_mask:0xf
	v_fmac_f32_dpp v119, v7, v59 row_shr:2 row_mask:0xf bank_mask:0xf
	v_fmac_f32_dpp v116, v0, v220 row_ror:1 row_mask:0xf bank_mask:0xf bound_ctrl:1
	v_fmac_f32_dpp v117, v1, v221 row_ror:1 row_mask:0xf bank_mask:0xf bound_ctrl:1
	v_fmac_f32_dpp v118, v2, v222 row_ror:1 row_mask:0xf bank_mask:0xf bound_ctrl:1
	v_fmac_f32_dpp v119, v3, v223 row_ror:1 row_mask:0xf bank_mask:0xf bound_ctrl:1
	v_fmac_f32_dpp v116, v0, v224 row_ror:2 row_mask:0xf bank_mask:0xf bound_ctrl:1
	v_fmac_f32_dpp v117, v1, v225 row_ror:2 row_mask:0xf bank_mask:0xf bound_ctrl:1
	v_fmac_f32_dpp v118, v2, v226 row_ror:2 row_mask:0xf bank_mask:0xf bound_ctrl:1
	v_fmac_f32_dpp v119, v3, v227 row_ror:2 row_mask:0xf bank_mask:0xf bound_ctrl:1
	s_nop 0
	s_waitcnt lgkmcnt(0)
	v_pk_fma_f32 v[230:231], v[108:109], v[0:1], v[112:113]
	v_pk_fma_f32 v[232:233], v[110:111], v[2:3], v[114:115]
	s_nop 0
	v_fmac_f32_dpp v230, v0, v60 row_shr:1 row_mask:0xf bank_mask:0xf
	v_fmac_f32_dpp v231, v1, v61 row_shr:1 row_mask:0xf bank_mask:0xf
	v_fmac_f32_dpp v232, v2, v62 row_shr:1 row_mask:0xf bank_mask:0xf
	v_fmac_f32_dpp v233, v3, v63 row_shr:1 row_mask:0xf bank_mask:0xf
	v_fmac_f32_dpp v230, v0, v56 row_shr:2 row_mask:0xf bank_mask:0xf
	v_fmac_f32_dpp v231, v1, v57 row_shr:2 row_mask:0xf bank_mask:0xf
	v_fmac_f32_dpp v232, v2, v58 row_shr:2 row_mask:0xf bank_mask:0xf
	v_fmac_f32_dpp v233, v3, v59 row_shr:2 row_mask:0xf bank_mask:0xf
	v_fmac_f32_dpp v230, v104, v220 row_ror:1 row_mask:0xf bank_mask:0xf bound_ctrl:1
	v_fmac_f32_dpp v231, v105, v221 row_ror:1 row_mask:0xf bank_mask:0xf bound_ctrl:1
	v_fmac_f32_dpp v232, v106, v222 row_ror:1 row_mask:0xf bank_mask:0xf bound_ctrl:1
	v_fmac_f32_dpp v233, v107, v223 row_ror:1 row_mask:0xf bank_mask:0xf bound_ctrl:1
	v_fmac_f32_dpp v230, v104, v224 row_ror:2 row_mask:0xf bank_mask:0xf bound_ctrl:1
	v_fmac_f32_dpp v231, v105, v225 row_ror:2 row_mask:0xf bank_mask:0xf bound_ctrl:1
	v_fmac_f32_dpp v232, v106, v226 row_ror:2 row_mask:0xf bank_mask:0xf bound_ctrl:1
	v_fmac_f32_dpp v233, v107, v227 row_ror:2 row_mask:0xf bank_mask:0xf bound_ctrl:1
	v_mov_b64_e32 v[104:105], v[230:231]
	v_mov_b64_e32 v[106:107], v[232:233]
	s_nop 0
	ds_read_b128 v[120:123], v212 offset:4624
	v_pk_fma_f32 v[0:1], v[108:109], v[36:37], v[112:113]
	v_pk_fma_f32 v[2:3], v[110:111], v[38:39], v[114:115]
	s_nop 0
	v_fmac_f32_dpp v0, v36, v60 row_shr:1 row_mask:0xf bank_mask:0xf
	v_fmac_f32_dpp v1, v37, v61 row_shr:1 row_mask:0xf bank_mask:0xf
	v_fmac_f32_dpp v2, v38, v62 row_shr:1 row_mask:0xf bank_mask:0xf
	v_fmac_f32_dpp v3, v39, v63 row_shr:1 row_mask:0xf bank_mask:0xf
	v_fmac_f32_dpp v0, v36, v56 row_shr:2 row_mask:0xf bank_mask:0xf
	v_fmac_f32_dpp v1, v37, v57 row_shr:2 row_mask:0xf bank_mask:0xf
	v_fmac_f32_dpp v2, v38, v58 row_shr:2 row_mask:0xf bank_mask:0xf
	v_fmac_f32_dpp v3, v39, v59 row_shr:2 row_mask:0xf bank_mask:0xf
	v_fmac_f32_dpp v0, v28, v220 row_ror:1 row_mask:0xf bank_mask:0xf bound_ctrl:1
	v_fmac_f32_dpp v1, v29, v221 row_ror:1 row_mask:0xf bank_mask:0xf bound_ctrl:1
	v_fmac_f32_dpp v2, v30, v222 row_ror:1 row_mask:0xf bank_mask:0xf bound_ctrl:1
	v_fmac_f32_dpp v3, v31, v223 row_ror:1 row_mask:0xf bank_mask:0xf bound_ctrl:1
	v_fmac_f32_dpp v0, v28, v224 row_ror:2 row_mask:0xf bank_mask:0xf bound_ctrl:1
	v_fmac_f32_dpp v1, v29, v225 row_ror:2 row_mask:0xf bank_mask:0xf bound_ctrl:1
	v_fmac_f32_dpp v2, v30, v226 row_ror:2 row_mask:0xf bank_mask:0xf bound_ctrl:1
	v_fmac_f32_dpp v3, v31, v227 row_ror:2 row_mask:0xf bank_mask:0xf bound_ctrl:1
	s_nop 0
	v_pk_fma_f32 v[4:5], v[108:109], v[28:29], v[112:113]
	v_pk_fma_f32 v[6:7], v[110:111], v[30:31], v[114:115]
	s_nop 0
	v_fmac_f32_dpp v4, v28, v60 row_shr:1 row_mask:0xf bank_mask:0xf
	v_fmac_f32_dpp v5, v29, v61 row_shr:1 row_mask:0xf bank_mask:0xf
	v_fmac_f32_dpp v6, v30, v62 row_shr:1 row_mask:0xf bank_mask:0xf
	v_fmac_f32_dpp v7, v31, v63 row_shr:1 row_mask:0xf bank_mask:0xf
	v_fmac_f32_dpp v4, v28, v56 row_shr:2 row_mask:0xf bank_mask:0xf
	v_fmac_f32_dpp v5, v29, v57 row_shr:2 row_mask:0xf bank_mask:0xf
	v_fmac_f32_dpp v6, v30, v58 row_shr:2 row_mask:0xf bank_mask:0xf
	v_fmac_f32_dpp v7, v31, v59 row_shr:2 row_mask:0xf bank_mask:0xf
	v_fmac_f32_dpp v4, v16, v220 row_ror:1 row_mask:0xf bank_mask:0xf bound_ctrl:1
	v_fmac_f32_dpp v5, v17, v221 row_ror:1 row_mask:0xf bank_mask:0xf bound_ctrl:1
	v_fmac_f32_dpp v6, v18, v222 row_ror:1 row_mask:0xf bank_mask:0xf bound_ctrl:1
	v_fmac_f32_dpp v7, v19, v223 row_ror:1 row_mask:0xf bank_mask:0xf bound_ctrl:1
	v_fmac_f32_dpp v4, v16, v224 row_ror:2 row_mask:0xf bank_mask:0xf bound_ctrl:1
	v_fmac_f32_dpp v5, v17, v225 row_ror:2 row_mask:0xf bank_mask:0xf bound_ctrl:1
	v_fmac_f32_dpp v6, v18, v226 row_ror:2 row_mask:0xf bank_mask:0xf bound_ctrl:1
	v_fmac_f32_dpp v7, v19, v227 row_ror:2 row_mask:0xf bank_mask:0xf bound_ctrl:1
	s_nop 0
	v_pk_fma_f32 v[230:231], v[108:109], v[16:17], v[112:113]
	v_pk_fma_f32 v[232:233], v[110:111], v[18:19], v[114:115]
	s_nop 0
	v_fmac_f32_dpp v230, v16, v60 row_shr:1 row_mask:0xf bank_mask:0xf
	v_fmac_f32_dpp v231, v17, v61 row_shr:1 row_mask:0xf bank_mask:0xf
	v_fmac_f32_dpp v232, v18, v62 row_shr:1 row_mask:0xf bank_mask:0xf
	v_fmac_f32_dpp v233, v19, v63 row_shr:1 row_mask:0xf bank_mask:0xf
	v_fmac_f32_dpp v230, v16, v56 row_shr:2 row_mask:0xf bank_mask:0xf
	v_fmac_f32_dpp v231, v17, v57 row_shr:2 row_mask:0xf bank_mask:0xf
	v_fmac_f32_dpp v232, v18, v58 row_shr:2 row_mask:0xf bank_mask:0xf
	v_fmac_f32_dpp v233, v19, v59 row_shr:2 row_mask:0xf bank_mask:0xf
	v_fmac_f32_dpp v230, v8, v220 row_ror:1 row_mask:0xf bank_mask:0xf bound_ctrl:1
	v_fmac_f32_dpp v231, v9, v221 row_ror:1 row_mask:0xf bank_mask:0xf bound_ctrl:1
	v_fmac_f32_dpp v232, v10, v222 row_ror:1 row_mask:0xf bank_mask:0xf bound_ctrl:1
	v_fmac_f32_dpp v233, v11, v223 row_ror:1 row_mask:0xf bank_mask:0xf bound_ctrl:1
	v_fmac_f32_dpp v230, v8, v224 row_ror:2 row_mask:0xf bank_mask:0xf bound_ctrl:1
	v_fmac_f32_dpp v231, v9, v225 row_ror:2 row_mask:0xf bank_mask:0xf bound_ctrl:1
	v_fmac_f32_dpp v232, v10, v226 row_ror:2 row_mask:0xf bank_mask:0xf bound_ctrl:1
	v_fmac_f32_dpp v233, v11, v227 row_ror:2 row_mask:0xf bank_mask:0xf bound_ctrl:1
	v_mov_b64_e32 v[16:17], v[230:231]
	v_mov_b64_e32 v[18:19], v[232:233]
	s_nop 0
	s_waitcnt lgkmcnt(0)
	v_pk_fma_f32 v[36:37], v[108:109], v[8:9], v[112:113]
	v_pk_fma_f32 v[38:39], v[110:111], v[10:11], v[114:115]
	s_nop 0
	v_fmac_f32_dpp v36, v8, v60 row_shr:1 row_mask:0xf bank_mask:0xf
	v_fmac_f32_dpp v37, v9, v61 row_shr:1 row_mask:0xf bank_mask:0xf
	v_fmac_f32_dpp v38, v10, v62 row_shr:1 row_mask:0xf bank_mask:0xf
	v_fmac_f32_dpp v39, v11, v63 row_shr:1 row_mask:0xf bank_mask:0xf
	v_fmac_f32_dpp v36, v8, v56 row_shr:2 row_mask:0xf bank_mask:0xf
	v_fmac_f32_dpp v37, v9, v57 row_shr:2 row_mask:0xf bank_mask:0xf
	v_fmac_f32_dpp v38, v10, v58 row_shr:2 row_mask:0xf bank_mask:0xf
	v_fmac_f32_dpp v39, v11, v59 row_shr:2 row_mask:0xf bank_mask:0xf
	v_fmac_f32_dpp v36, v120, v220 row_ror:1 row_mask:0xf bank_mask:0xf bound_ctrl:1
	v_fmac_f32_dpp v37, v121, v221 row_ror:1 row_mask:0xf bank_mask:0xf bound_ctrl:1
	v_fmac_f32_dpp v38, v122, v222 row_ror:1 row_mask:0xf bank_mask:0xf bound_ctrl:1
	v_fmac_f32_dpp v39, v123, v223 row_ror:1 row_mask:0xf bank_mask:0xf bound_ctrl:1
	v_fmac_f32_dpp v36, v120, v224 row_ror:2 row_mask:0xf bank_mask:0xf bound_ctrl:1
	v_fmac_f32_dpp v37, v121, v225 row_ror:2 row_mask:0xf bank_mask:0xf bound_ctrl:1
	v_fmac_f32_dpp v38, v122, v226 row_ror:2 row_mask:0xf bank_mask:0xf bound_ctrl:1
	v_fmac_f32_dpp v39, v123, v227 row_ror:2 row_mask:0xf bank_mask:0xf bound_ctrl:1
	s_nop 0
	v_mul_f32_e32 v8, v100, v100
	v_mul_f32_e32 v9, v101, v101
	v_mul_f32_e32 v10, v102, v102
	v_mul_f32_e32 v11, v103, v103
	v_fmamk_f32 v8, v8, 0xbdd2d3e2, v215
	v_fmamk_f32 v9, v9, 0xbdd2d3e2, v215
	v_fmamk_f32 v10, v10, 0xbdd2d3e2, v215
	v_fmamk_f32 v11, v11, 0xbdd2d3e2, v215
	v_mul_f32_e32 v8, v100, v8
	v_mul_f32_e32 v9, v101, v9
	v_mul_f32_e32 v10, v102, v10
	v_mul_f32_e32 v11, v103, v11
	v_exp_f32_e32 v8, v8
	v_exp_f32_e32 v9, v9
	v_exp_f32_e32 v10, v10
	v_exp_f32_e32 v11, v11
	v_add_f32_e32 v8, 1.0, v8
	v_add_f32_e32 v9, 1.0, v9
	v_add_f32_e32 v10, 1.0, v10
	v_add_f32_e32 v11, 1.0, v11
	v_rcp_f32_e32 v8, v8
	v_rcp_f32_e32 v9, v9
	v_rcp_f32_e32 v10, v10
	v_rcp_f32_e32 v11, v11
	v_pk_mul_f32 v[8:9], v[100:101], v[8:9]
	s_nop 0
	v_pk_mul_f32 v[8:9], v[8:9], v[104:105]
	v_pk_mul_f32 v[10:11], v[102:103], v[10:11]
	s_nop 0
	v_pk_mul_f32 v[10:11], v[10:11], v[106:107]
	s_nop 0
	v_mul_f32_e32 v28, v96, v96
	v_mul_f32_e32 v29, v97, v97
	v_mul_f32_e32 v30, v98, v98
	v_mul_f32_e32 v31, v99, v99
	v_fmamk_f32 v28, v28, 0xbdd2d3e2, v215
	v_fmamk_f32 v29, v29, 0xbdd2d3e2, v215
	v_fmamk_f32 v30, v30, 0xbdd2d3e2, v215
	v_fmamk_f32 v31, v31, 0xbdd2d3e2, v215
	v_mul_f32_e32 v28, v96, v28
	v_mul_f32_e32 v29, v97, v29
	v_mul_f32_e32 v30, v98, v30
	v_mul_f32_e32 v31, v99, v31
	v_exp_f32_e32 v28, v28
	v_exp_f32_e32 v29, v29
	v_exp_f32_e32 v30, v30
	v_exp_f32_e32 v31, v31
	v_add_f32_e32 v28, 1.0, v28
	v_add_f32_e32 v29, 1.0, v29
	v_add_f32_e32 v30, 1.0, v30
	v_add_f32_e32 v31, 1.0, v31
	v_rcp_f32_e32 v28, v28
	v_rcp_f32_e32 v29, v29
	v_rcp_f32_e32 v30, v30
	v_rcp_f32_e32 v31, v31
	v_pk_mul_f32 v[28:29], v[96:97], v[28:29]
	s_nop 0
	v_pk_mul_f32 v[28:29], v[28:29], v[116:117]
	v_pk_mul_f32 v[30:31], v[98:99], v[30:31]
	s_nop 0
	v_pk_mul_f32 v[30:31], v[30:31], v[118:119]
	s_nop 0
	v_mul_f32_e32 v56, v44, v44
	v_mul_f32_e32 v57, v45, v45
	v_mul_f32_e32 v58, v46, v46
	v_mul_f32_e32 v59, v47, v47
	v_fmamk_f32 v56, v56, 0xbdd2d3e2, v215
	v_fmamk_f32 v57, v57, 0xbdd2d3e2, v215
	v_fmamk_f32 v58, v58, 0xbdd2d3e2, v215
	v_fmamk_f32 v59, v59, 0xbdd2d3e2, v215
	v_mul_f32_e32 v56, v44, v56
	v_mul_f32_e32 v57, v45, v57
	v_mul_f32_e32 v58, v46, v58
	v_mul_f32_e32 v59, v47, v59
	v_exp_f32_e32 v56, v56
	v_exp_f32_e32 v57, v57
	v_exp_f32_e32 v58, v58
	v_exp_f32_e32 v59, v59
	v_add_f32_e32 v56, 1.0, v56
	v_add_f32_e32 v57, 1.0, v57
	v_add_f32_e32 v58, 1.0, v58
	v_add_f32_e32 v59, 1.0, v59
	v_rcp_f32_e32 v56, v56
	v_rcp_f32_e32 v57, v57
	v_rcp_f32_e32 v58, v58
	v_rcp_f32_e32 v59, v59
	v_pk_mul_f32 v[44:45], v[44:45], v[56:57]
	s_nop 0
	v_pk_mul_f32 v[12:13], v[44:45], v[12:13]
	v_pk_mul_f32 v[46:47], v[46:47], v[58:59]
	s_nop 0
	v_pk_mul_f32 v[14:15], v[46:47], v[14:15]
	s_nop 0
	v_mul_f32_e32 v44, v52, v52
	v_mul_f32_e32 v45, v53, v53
	v_mul_f32_e32 v46, v54, v54
	v_mul_f32_e32 v47, v55, v55
	v_fmamk_f32 v44, v44, 0xbdd2d3e2, v215
	v_fmamk_f32 v45, v45, 0xbdd2d3e2, v215
	v_fmamk_f32 v46, v46, 0xbdd2d3e2, v215
	v_fmamk_f32 v47, v47, 0xbdd2d3e2, v215
	v_mul_f32_e32 v44, v52, v44
	v_mul_f32_e32 v45, v53, v45
	v_mul_f32_e32 v46, v54, v46
	v_mul_f32_e32 v47, v55, v47
	v_exp_f32_e32 v44, v44
	v_exp_f32_e32 v45, v45
	v_exp_f32_e32 v46, v46
	v_exp_f32_e32 v47, v47
	v_add_f32_e32 v44, 1.0, v44
	v_add_f32_e32 v45, 1.0, v45
	v_add_f32_e32 v46, 1.0, v46
	v_add_f32_e32 v47, 1.0, v47
	v_rcp_f32_e32 v44, v44
	v_rcp_f32_e32 v45, v45
	v_rcp_f32_e32 v46, v46
	v_rcp_f32_e32 v47, v47
	v_pk_mul_f32 v[44:45], v[52:53], v[44:45]
	s_nop 0
	v_pk_mul_f32 v[20:21], v[44:45], v[20:21]
	v_pk_mul_f32 v[46:47], v[54:55], v[46:47]
	s_nop 0
	v_pk_mul_f32 v[22:23], v[46:47], v[22:23]
	s_nop 0
	v_mul_f32_e32 v44, v40, v40
	v_mul_f32_e32 v45, v41, v41
	v_mul_f32_e32 v46, v42, v42
	v_mul_f32_e32 v47, v43, v43
	v_fmamk_f32 v44, v44, 0xbdd2d3e2, v215
	v_fmamk_f32 v45, v45, 0xbdd2d3e2, v215
	v_fmamk_f32 v46, v46, 0xbdd2d3e2, v215
	v_fmamk_f32 v47, v47, 0xbdd2d3e2, v215
	v_mul_f32_e32 v44, v40, v44
	v_mul_f32_e32 v45, v41, v45
	v_mul_f32_e32 v46, v42, v46
	v_mul_f32_e32 v47, v43, v47
	v_exp_f32_e32 v44, v44
	v_exp_f32_e32 v45, v45
	v_exp_f32_e32 v46, v46
	v_exp_f32_e32 v47, v47
	v_add_f32_e32 v44, 1.0, v44
	v_add_f32_e32 v45, 1.0, v45
	v_add_f32_e32 v46, 1.0, v46
	v_add_f32_e32 v47, 1.0, v47
	v_rcp_f32_e32 v44, v44
	v_rcp_f32_e32 v45, v45
	v_rcp_f32_e32 v46, v46
	v_rcp_f32_e32 v47, v47
	v_pk_mul_f32 v[40:41], v[40:41], v[44:45]
	s_nop 0
	v_pk_mul_f32 v[36:37], v[40:41], v[36:37]
	v_pk_mul_f32 v[42:43], v[42:43], v[46:47]
	s_nop 0
	v_pk_mul_f32 v[38:39], v[42:43], v[38:39]
	s_nop 0
	v_mul_f32_e32 v40, v48, v48
	v_mul_f32_e32 v41, v49, v49
	v_mul_f32_e32 v42, v50, v50
	v_mul_f32_e32 v43, v51, v51
	v_fmamk_f32 v40, v40, 0xbdd2d3e2, v215
	v_fmamk_f32 v41, v41, 0xbdd2d3e2, v215
	v_fmamk_f32 v42, v42, 0xbdd2d3e2, v215
	v_fmamk_f32 v43, v43, 0xbdd2d3e2, v215
	v_mul_f32_e32 v40, v48, v40
	v_mul_f32_e32 v41, v49, v41
	v_mul_f32_e32 v42, v50, v42
	v_mul_f32_e32 v43, v51, v43
	v_exp_f32_e32 v40, v40
	v_exp_f32_e32 v41, v41
	v_exp_f32_e32 v42, v42
	v_exp_f32_e32 v43, v43
	v_add_f32_e32 v40, 1.0, v40
	v_add_f32_e32 v41, 1.0, v41
	v_add_f32_e32 v42, 1.0, v42
	v_add_f32_e32 v43, 1.0, v43
	v_rcp_f32_e32 v40, v40
	v_rcp_f32_e32 v41, v41
	v_rcp_f32_e32 v42, v42
	v_rcp_f32_e32 v43, v43
	v_pk_mul_f32 v[40:41], v[48:49], v[40:41]
	s_nop 0
	v_pk_mul_f32 v[16:17], v[40:41], v[16:17]
	v_pk_mul_f32 v[42:43], v[50:51], v[42:43]
	s_nop 0
	v_pk_mul_f32 v[18:19], v[42:43], v[18:19]
	s_nop 0
	v_mul_f32_e32 v40, v32, v32
	v_mul_f32_e32 v41, v33, v33
	v_mul_f32_e32 v42, v34, v34
	v_mul_f32_e32 v43, v35, v35
	v_fmamk_f32 v40, v40, 0xbdd2d3e2, v215
	v_fmamk_f32 v41, v41, 0xbdd2d3e2, v215
	v_fmamk_f32 v42, v42, 0xbdd2d3e2, v215
	v_fmamk_f32 v43, v43, 0xbdd2d3e2, v215
	v_mul_f32_e32 v40, v32, v40
	v_mul_f32_e32 v41, v33, v41
	v_mul_f32_e32 v42, v34, v42
	v_mul_f32_e32 v43, v35, v43
	v_exp_f32_e32 v40, v40
	v_exp_f32_e32 v41, v41
	v_exp_f32_e32 v42, v42
	v_exp_f32_e32 v43, v43
	v_add_f32_e32 v40, 1.0, v40
	v_add_f32_e32 v41, 1.0, v41
	v_add_f32_e32 v42, 1.0, v42
	v_add_f32_e32 v43, 1.0, v43
	v_rcp_f32_e32 v40, v40
	v_rcp_f32_e32 v41, v41
	v_rcp_f32_e32 v42, v42
	v_rcp_f32_e32 v43, v43
	v_pk_mul_f32 v[32:33], v[32:33], v[40:41]
	s_nop 0
	v_pk_mul_f32 v[4:5], v[32:33], v[4:5]
	v_pk_mul_f32 v[34:35], v[34:35], v[42:43]
	s_nop 0
	v_pk_mul_f32 v[6:7], v[34:35], v[6:7]
	s_nop 0
	v_mul_f32_e32 v32, v24, v24
	v_mul_f32_e32 v33, v25, v25
	v_mul_f32_e32 v34, v26, v26
	v_mul_f32_e32 v35, v27, v27
	v_fmamk_f32 v32, v32, 0xbdd2d3e2, v215
	v_fmamk_f32 v33, v33, 0xbdd2d3e2, v215
	v_fmamk_f32 v34, v34, 0xbdd2d3e2, v215
	v_fmamk_f32 v35, v35, 0xbdd2d3e2, v215
	v_mul_f32_e32 v32, v24, v32
	v_mul_f32_e32 v33, v25, v33
	v_mul_f32_e32 v34, v26, v34
	v_mul_f32_e32 v35, v27, v35
	v_exp_f32_e32 v32, v32
	v_exp_f32_e32 v33, v33
	v_exp_f32_e32 v34, v34
	v_exp_f32_e32 v35, v35
	v_add_f32_e32 v32, 1.0, v32
	v_add_f32_e32 v33, 1.0, v33
	v_add_f32_e32 v34, 1.0, v34
	v_add_f32_e32 v35, 1.0, v35
	v_rcp_f32_e32 v32, v32
	v_rcp_f32_e32 v33, v33
	v_rcp_f32_e32 v34, v34
	v_rcp_f32_e32 v35, v35
	v_pk_mul_f32 v[24:25], v[24:25], v[32:33]
	s_nop 0
	v_pk_mul_f32 v[0:1], v[24:25], v[0:1]
	v_pk_mul_f32 v[26:27], v[26:27], v[34:35]
	s_nop 0
	v_pk_mul_f32 v[2:3], v[26:27], v[2:3]
	s_nop 0
	s_ashr_i32 s61, s60, 31
	s_ashr_i32 s29, s28, 31
	s_and_saveexec_b64 s[8:9], s[2:3]
	s_cbranch_execz .LBB0_999
	v_cvt_pk_bf16_f32 v26, v8, v9
	v_cvt_pk_bf16_f32 v27, v10, v11
	v_lshl_add_u64 v[8:9], s[60:61], 0, v[178:179]
	v_mov_b64_e32 v[10:11], s[18:19]
	v_mad_u64_u32 v[10:11], s[14:15], v8, s89, v[10:11]
	v_mad_i32_i24 v11, v9, s89, v11
	v_lshl_add_u64 v[8:9], s[28:29], 1, v[10:11]
	v_cvt_pk_bf16_f32 v24, v64, v65
	v_cvt_pk_bf16_f32 v25, v66, v67
	v_lshl_add_u64 v[8:9], v[8:9], 0, v[172:173]
	global_store_dwordx4 v[8:9], v[24:27], off nt
